# P1 epilogue unswitched on the activation kind: straight-line specialised copies (act 0/1/2/3) extracted from the generic code, dead flag code removed
# speedup vs baseline: 1.0114x; 1.0114x over previous
.LBB0_185:
	s_and_b64 vcc, exec, s[54:55]
	s_cbranch_vccnz .Lmy_e1_generic
	s_and_b64 vcc, exec, s[74:75]
	s_cbranch_vccnz .Lmy_e1_act1
	s_and_b64 vcc, exec, s[76:77]
	s_cbranch_vccnz .Lmy_e1_act2
	s_and_b64 vcc, exec, s[56:57]
	s_cbranch_vccz .Lmy_e1_act3
	s_xor_b64 s[74:75], s[74:75], -1
	s_xor_b64 s[76:77], s[76:77], -1
	v_mov_b32_e32 v162, 0
	v_mov_b32_e32 v149, v129
	v_mov_b32_e32 v148, v128
	v_mov_b32_e32 v147, v127
	v_mov_b32_e32 v146, v126
	v_mov_b32_e32 v153, v125
	v_mov_b32_e32 v152, v124
	v_mov_b32_e32 v151, v123
	v_mov_b32_e32 v150, v122
	s_mov_b64 s[78:79], 0
	s_lshl_b32 s6, s6, 8
	s_add_i32 s6, s7, s6
	v_or_b32_e32 v122, s6, v156
	s_lshl_b32 s6, s72, 1
	s_add_u32 s6, s38, s6
	v_lshl_add_u32 v161, s8, 8, v154
	s_addc_u32 s7, s39, 0
	v_ashrrev_i32_e32 v123, 31, v122
	v_lshl_add_u64 v[122:123], v[122:123], 1, s[6:7]
	v_mad_i64_i32 v[124:125], s[6:7], s70, v161, 0
	v_lshl_add_u64 v[124:125], v[124:125], 1, v[122:123]
	v_cvt_pk_bf16_f32 v126, v146, v147
	v_cvt_pk_bf16_f32 v127, v148, v149
	v_cvt_pk_bf16_f32 v128, v150, v151
	v_cvt_pk_bf16_f32 v129, v152, v153
	global_store_dwordx4 v[124:125], v[126:129], off
	v_mov_b32_e32 v150, v162
	s_nop 0
	v_mov_b32_e32 v129, v121
	v_mov_b32_e32 v128, v120
	v_mov_b32_e32 v127, v119
	v_mov_b32_e32 v126, v118
	v_mov_b32_e32 v149, v117
	v_mov_b32_e32 v148, v116
	v_mov_b32_e32 v147, v115
	v_mov_b32_e32 v146, v114
	v_cvt_pk_bf16_f32 v114, v126, v127
	v_cvt_pk_bf16_f32 v115, v128, v129
	v_cvt_pk_bf16_f32 v116, v146, v147
	v_cvt_pk_bf16_f32 v117, v148, v149
	global_store_dwordx4 v[124:125], v[114:117], off offset:256
	v_mov_b32_e32 v124, v150
	s_nop 0
	v_mov_b32_e32 v117, v113
	v_mov_b32_e32 v116, v112
	v_mov_b32_e32 v115, v111
	v_mov_b32_e32 v114, v110
	v_mov_b32_e32 v121, v109
	v_mov_b32_e32 v120, v108
	v_mov_b32_e32 v119, v107
	v_mov_b32_e32 v118, v106
	v_or_b32_e32 v106, 16, v161
	v_mad_i64_i32 v[106:107], s[72:73], s70, v106, 0
	v_lshl_add_u64 v[106:107], v[106:107], 1, v[122:123]
	v_cvt_pk_bf16_f32 v108, v114, v115
	v_cvt_pk_bf16_f32 v109, v116, v117
	v_cvt_pk_bf16_f32 v110, v118, v119
	v_cvt_pk_bf16_f32 v111, v120, v121
	global_store_dwordx4 v[106:107], v[108:111], off
	v_mov_b32_e32 v116, v124
	s_nop 0
	v_mov_b32_e32 v111, v105
	v_mov_b32_e32 v110, v104
	v_mov_b32_e32 v109, v103
	v_mov_b32_e32 v108, v102
	v_mov_b32_e32 v115, v101
	v_mov_b32_e32 v114, v100
	v_mov_b32_e32 v113, v99
	v_mov_b32_e32 v112, v98
	v_cvt_pk_bf16_f32 v98, v108, v109
	v_cvt_pk_bf16_f32 v99, v110, v111
	v_cvt_pk_bf16_f32 v100, v112, v113
	v_cvt_pk_bf16_f32 v101, v114, v115
	global_store_dwordx4 v[106:107], v[98:101], off offset:256
	v_mov_b32_e32 v106, v116
	s_nop 0
	v_mov_b32_e32 v101, v97
	v_mov_b32_e32 v100, v96
	v_mov_b32_e32 v99, v95
	v_mov_b32_e32 v98, v94
	v_mov_b32_e32 v105, v93
	v_mov_b32_e32 v104, v92
	v_mov_b32_e32 v103, v91
	v_mov_b32_e32 v102, v90
	v_or_b32_e32 v90, 32, v161
	v_mad_i64_i32 v[90:91], s[72:73], s70, v90, 0
	v_lshl_add_u64 v[90:91], v[90:91], 1, v[122:123]
	v_cvt_pk_bf16_f32 v92, v98, v99
	v_cvt_pk_bf16_f32 v93, v100, v101
	v_cvt_pk_bf16_f32 v94, v102, v103
	v_cvt_pk_bf16_f32 v95, v104, v105
	global_store_dwordx4 v[90:91], v[92:95], off
	v_mov_b32_e32 v100, v106
	s_nop 0
	v_mov_b32_e32 v95, v89
	v_mov_b32_e32 v94, v88
	v_mov_b32_e32 v93, v87
	v_mov_b32_e32 v92, v86
	v_mov_b32_e32 v99, v85
	v_mov_b32_e32 v98, v84
	v_mov_b32_e32 v97, v83
	v_mov_b32_e32 v96, v82
	v_cvt_pk_bf16_f32 v82, v92, v93
	v_cvt_pk_bf16_f32 v83, v94, v95
	v_cvt_pk_bf16_f32 v84, v96, v97
	v_cvt_pk_bf16_f32 v85, v98, v99
	global_store_dwordx4 v[90:91], v[82:85], off offset:256
	v_mov_b32_e32 v90, v100
	s_nop 0
	v_mov_b32_e32 v85, v81
	v_mov_b32_e32 v84, v80
	v_mov_b32_e32 v83, v79
	v_mov_b32_e32 v82, v78
	v_mov_b32_e32 v89, v77
	v_mov_b32_e32 v88, v76
	v_mov_b32_e32 v87, v75
	v_mov_b32_e32 v86, v74
	v_or_b32_e32 v74, 48, v161
	v_mad_i64_i32 v[74:75], s[72:73], s70, v74, 0
	v_lshl_add_u64 v[74:75], v[74:75], 1, v[122:123]
	v_cvt_pk_bf16_f32 v76, v82, v83
	v_cvt_pk_bf16_f32 v77, v84, v85
	v_cvt_pk_bf16_f32 v78, v86, v87
	v_cvt_pk_bf16_f32 v79, v88, v89
	global_store_dwordx4 v[74:75], v[76:79], off
	v_mov_b32_e32 v84, v90
	s_nop 0
	v_mov_b32_e32 v79, v73
	v_mov_b32_e32 v78, v72
	v_mov_b32_e32 v77, v71
	v_mov_b32_e32 v76, v70
	v_mov_b32_e32 v83, v69
	v_mov_b32_e32 v82, v68
	v_mov_b32_e32 v81, v67
	v_mov_b32_e32 v80, v66
	v_cvt_pk_bf16_f32 v66, v76, v77
	v_cvt_pk_bf16_f32 v67, v78, v79
	v_cvt_pk_bf16_f32 v68, v80, v81
	v_cvt_pk_bf16_f32 v69, v82, v83
	global_store_dwordx4 v[74:75], v[66:69], off offset:256
	v_mov_b32_e32 v74, v84
	s_nop 0
	v_mov_b32_e32 v69, v65
	v_mov_b32_e32 v68, v64
	v_mov_b32_e32 v67, v63
	v_mov_b32_e32 v66, v62
	v_mov_b32_e32 v73, v61
	v_mov_b32_e32 v72, v60
	v_mov_b32_e32 v71, v59
	v_mov_b32_e32 v70, v58
	v_add_u32_e32 v58, 0x80, v161
	v_mad_i64_i32 v[58:59], s[72:73], s70, v58, 0
	v_lshl_add_u64 v[58:59], v[58:59], 1, v[122:123]
	v_cvt_pk_bf16_f32 v60, v66, v67
	v_cvt_pk_bf16_f32 v61, v68, v69
	v_cvt_pk_bf16_f32 v62, v70, v71
	v_cvt_pk_bf16_f32 v63, v72, v73
	global_store_dwordx4 v[58:59], v[60:63], off
	v_mov_b32_e32 v68, v74
	s_nop 0
	v_mov_b32_e32 v63, v57
	v_mov_b32_e32 v62, v56
	v_mov_b32_e32 v61, v55
	v_mov_b32_e32 v60, v54
	v_mov_b32_e32 v67, v53
	v_mov_b32_e32 v66, v52
	v_mov_b32_e32 v65, v51
	v_mov_b32_e32 v64, v50
	v_cvt_pk_bf16_f32 v50, v60, v61
	v_cvt_pk_bf16_f32 v51, v62, v63
	v_cvt_pk_bf16_f32 v52, v64, v65
	v_cvt_pk_bf16_f32 v53, v66, v67
	global_store_dwordx4 v[58:59], v[50:53], off offset:256
	v_mov_b32_e32 v58, v68
	s_nop 0
	v_mov_b32_e32 v53, v49
	v_mov_b32_e32 v52, v48
	v_mov_b32_e32 v51, v47
	v_mov_b32_e32 v50, v46
	v_mov_b32_e32 v57, v45
	v_mov_b32_e32 v56, v44
	v_mov_b32_e32 v55, v43
	v_mov_b32_e32 v54, v42
	v_add_u32_e32 v42, 0x90, v161
	v_mad_i64_i32 v[42:43], s[72:73], s70, v42, 0
	v_lshl_add_u64 v[42:43], v[42:43], 1, v[122:123]
	v_cvt_pk_bf16_f32 v44, v50, v51
	v_cvt_pk_bf16_f32 v45, v52, v53
	v_cvt_pk_bf16_f32 v46, v54, v55
	v_cvt_pk_bf16_f32 v47, v56, v57
	global_store_dwordx4 v[42:43], v[44:47], off
	v_mov_b32_e32 v52, v58
	s_nop 0
	v_mov_b32_e32 v47, v41
	v_mov_b32_e32 v46, v40
	v_mov_b32_e32 v45, v39
	v_mov_b32_e32 v44, v38
	v_mov_b32_e32 v51, v37
	v_mov_b32_e32 v50, v36
	v_mov_b32_e32 v49, v35
	v_mov_b32_e32 v48, v34
	v_cvt_pk_bf16_f32 v34, v44, v45
	v_cvt_pk_bf16_f32 v35, v46, v47
	v_cvt_pk_bf16_f32 v36, v48, v49
	v_cvt_pk_bf16_f32 v37, v50, v51
	global_store_dwordx4 v[42:43], v[34:37], off offset:256
	v_mov_b32_e32 v42, v52
	s_nop 0
	v_mov_b32_e32 v37, v33
	v_mov_b32_e32 v36, v32
	v_mov_b32_e32 v35, v31
	v_mov_b32_e32 v34, v30
	v_mov_b32_e32 v41, v29
	v_mov_b32_e32 v40, v28
	v_mov_b32_e32 v39, v27
	v_mov_b32_e32 v38, v26
	v_add_u32_e32 v26, 0xa0, v161
	v_mad_i64_i32 v[26:27], s[72:73], s70, v26, 0
	v_lshl_add_u64 v[26:27], v[26:27], 1, v[122:123]
	v_cvt_pk_bf16_f32 v28, v34, v35
	v_cvt_pk_bf16_f32 v29, v36, v37
	v_cvt_pk_bf16_f32 v30, v38, v39
	v_cvt_pk_bf16_f32 v31, v40, v41
	global_store_dwordx4 v[26:27], v[28:31], off
	v_mov_b32_e32 v36, v42
	s_nop 0
	v_mov_b32_e32 v31, v25
	v_mov_b32_e32 v30, v24
	v_mov_b32_e32 v29, v23
	v_mov_b32_e32 v28, v22
	v_mov_b32_e32 v35, v21
	v_mov_b32_e32 v34, v20
	v_mov_b32_e32 v33, v19
	v_mov_b32_e32 v32, v18
	v_cvt_pk_bf16_f32 v18, v28, v29
	v_cvt_pk_bf16_f32 v19, v30, v31
	v_cvt_pk_bf16_f32 v20, v32, v33
	v_cvt_pk_bf16_f32 v21, v34, v35
	global_store_dwordx4 v[26:27], v[18:21], off offset:256
	v_mov_b32_e32 v26, v36
	s_nop 0
	v_mov_b32_e32 v21, v17
	v_mov_b32_e32 v20, v16
	v_mov_b32_e32 v19, v15
	v_mov_b32_e32 v18, v14
	v_mov_b32_e32 v25, v13
	v_mov_b32_e32 v24, v12
	v_mov_b32_e32 v23, v11
	v_mov_b32_e32 v22, v10
	s_mov_b64 s[72:73], 0
	v_add_u32_e32 v10, 0xb0, v161
	v_mad_i64_i32 v[10:11], s[70:71], s70, v10, 0
	v_lshl_add_u64 v[10:11], v[10:11], 1, v[122:123]
	v_cvt_pk_bf16_f32 v12, v18, v19
	v_cvt_pk_bf16_f32 v13, v20, v21
	v_cvt_pk_bf16_f32 v14, v22, v23
	v_cvt_pk_bf16_f32 v15, v24, v25
	global_store_dwordx4 v[10:11], v[12:15], off
	v_mov_b32_e32 v20, v26
	s_nop 0
	v_mov_b32_e32 v15, v9
	v_mov_b32_e32 v14, v8
	v_mov_b32_e32 v13, v7
	v_mov_b32_e32 v12, v6
	v_mov_b32_e32 v19, v5
	v_mov_b32_e32 v18, v4
	v_mov_b32_e32 v17, v3
	v_mov_b32_e32 v16, v2
	s_mov_b64 s[6:7], 0
	s_mov_b64 s[8:9], 0
	s_and_b64 vcc, exec, s[54:55]
	v_cvt_pk_bf16_f32 v2, v12, v13
	v_cvt_pk_bf16_f32 v3, v14, v15
	v_cvt_pk_bf16_f32 v4, v16, v17
	v_cvt_pk_bf16_f32 v5, v18, v19
	global_store_dwordx4 v[10:11], v[2:5], off offset:256
	s_branch .LBB0_416
.Lmy_e1_act1:
	s_xor_b64 s[74:75], s[74:75], -1
	s_mov_b64 s[78:79], -1
	s_xor_b64 s[76:77], s[76:77], -1
	v_mul_f32_e32 v147, 0xbfb8aa3b, v122
	v_mul_f32_e32 v148, 0xbfb8aa3b, v127
	v_exp_f32_e32 v147, v147
	v_exp_f32_e32 v148, v148
	v_mul_f32_e32 v149, 0xbfb8aa3b, v128
	v_mul_f32_e32 v151, 0xbfb8aa3b, v124
	v_add_f32_e32 v147, 1.0, v147
	v_rcp_f32_e32 v150, v147
	v_add_f32_e32 v147, 1.0, v148
	v_mul_f32_e32 v148, 0xbfb8aa3b, v123
	v_exp_f32_e32 v148, v148
	v_exp_f32_e32 v149, v149
	v_exp_f32_e32 v151, v151
	v_mul_f32_e32 v146, 0xbfb8aa3b, v126
	v_add_f32_e32 v161, 1.0, v148
	v_add_f32_e32 v148, 1.0, v149
	v_add_f32_e32 v149, 1.0, v151
	v_mul_f32_e32 v151, 0xbfb8aa3b, v129
	v_mul_f32_e32 v152, 0xbfb8aa3b, v125
	v_exp_f32_e32 v146, v146
	v_exp_f32_e32 v151, v151
	v_exp_f32_e32 v153, v152
	v_rcp_f32_e32 v152, v149
	v_add_f32_e32 v146, 1.0, v146
	v_add_f32_e32 v149, 1.0, v151
	v_add_f32_e32 v151, 1.0, v153
	v_rcp_f32_e32 v146, v146
	v_rcp_f32_e32 v147, v147
	v_rcp_f32_e32 v148, v148
	v_rcp_f32_e32 v149, v149
	v_rcp_f32_e32 v153, v151
	v_rcp_f32_e32 v151, v161
	v_pk_mul_f32 v[146:147], v[126:127], v[146:147]
	v_pk_mul_f32 v[148:149], v[128:129], v[148:149]
	v_pk_mul_f32 v[152:153], v[124:125], v[152:153]
	v_pk_mul_f32 v[150:151], v[122:123], v[150:151]
	v_mov_b32_e32 v162, 0
	s_lshl_b32 s6, s6, 8
	s_add_i32 s6, s7, s6
	v_or_b32_e32 v122, s6, v156
	s_lshl_b32 s6, s72, 1
	s_add_u32 s6, s38, s6
	v_lshl_add_u32 v161, s8, 8, v154
	s_addc_u32 s7, s39, 0
	v_ashrrev_i32_e32 v123, 31, v122
	v_lshl_add_u64 v[122:123], v[122:123], 1, s[6:7]
	v_mad_i64_i32 v[124:125], s[6:7], s70, v161, 0
	v_lshl_add_u64 v[124:125], v[124:125], 1, v[122:123]
	v_cvt_pk_bf16_f32 v126, v146, v147
	v_cvt_pk_bf16_f32 v127, v148, v149
	v_cvt_pk_bf16_f32 v128, v150, v151
	v_cvt_pk_bf16_f32 v129, v152, v153
	global_store_dwordx4 v[124:125], v[126:129], off
	s_nop 1
	v_cndmask_b32_e64 v126, 0, 1, s[76:77]
	v_cmp_ne_u32_e64 s[6:7], 1, v126
	v_mul_f32_e32 v127, 0xbfb8aa3b, v114
	v_mul_f32_e32 v128, 0xbfb8aa3b, v119
	v_exp_f32_e32 v127, v127
	v_exp_f32_e32 v128, v128
	v_mul_f32_e32 v129, 0xbfb8aa3b, v120
	v_mul_f32_e32 v147, 0xbfb8aa3b, v116
	v_add_f32_e32 v127, 1.0, v127
	v_rcp_f32_e32 v146, v127
	v_add_f32_e32 v127, 1.0, v128
	v_mul_f32_e32 v128, 0xbfb8aa3b, v115
	v_exp_f32_e32 v128, v128
	v_exp_f32_e32 v129, v129
	v_exp_f32_e32 v147, v147
	v_mul_f32_e32 v126, 0xbfb8aa3b, v118
	v_add_f32_e32 v150, 1.0, v128
	v_add_f32_e32 v128, 1.0, v129
	v_add_f32_e32 v129, 1.0, v147
	v_mul_f32_e32 v147, 0xbfb8aa3b, v121
	v_mul_f32_e32 v148, 0xbfb8aa3b, v117
	v_exp_f32_e32 v126, v126
	v_exp_f32_e32 v147, v147
	v_exp_f32_e32 v149, v148
	v_rcp_f32_e32 v148, v129
	v_add_f32_e32 v126, 1.0, v126
	v_add_f32_e32 v129, 1.0, v147
	v_add_f32_e32 v147, 1.0, v149
	v_rcp_f32_e32 v126, v126
	v_rcp_f32_e32 v127, v127
	v_rcp_f32_e32 v128, v128
	v_rcp_f32_e32 v129, v129
	v_rcp_f32_e32 v149, v147
	v_rcp_f32_e32 v147, v150
	v_pk_mul_f32 v[126:127], v[118:119], v[126:127]
	v_pk_mul_f32 v[128:129], v[120:121], v[128:129]
	v_pk_mul_f32 v[148:149], v[116:117], v[148:149]
	v_pk_mul_f32 v[146:147], v[114:115], v[146:147]
	v_mov_b32_e32 v150, v162
	v_cvt_pk_bf16_f32 v114, v126, v127
	v_cvt_pk_bf16_f32 v115, v128, v129
	v_cvt_pk_bf16_f32 v116, v146, v147
	v_cvt_pk_bf16_f32 v117, v148, v149
	global_store_dwordx4 v[124:125], v[114:117], off offset:256
	s_nop 1
	v_mul_f32_e32 v115, 0xbfb8aa3b, v106
	v_mul_f32_e32 v116, 0xbfb8aa3b, v111
	v_exp_f32_e32 v115, v115
	v_exp_f32_e32 v116, v116
	v_mul_f32_e32 v117, 0xbfb8aa3b, v112
	v_mul_f32_e32 v119, 0xbfb8aa3b, v108
	v_add_f32_e32 v115, 1.0, v115
	v_rcp_f32_e32 v118, v115
	v_add_f32_e32 v115, 1.0, v116
	v_mul_f32_e32 v116, 0xbfb8aa3b, v107
	v_exp_f32_e32 v116, v116
	v_exp_f32_e32 v117, v117
	v_exp_f32_e32 v119, v119
	v_mul_f32_e32 v114, 0xbfb8aa3b, v110
	v_add_f32_e32 v124, 1.0, v116
	v_add_f32_e32 v116, 1.0, v117
	v_add_f32_e32 v117, 1.0, v119
	v_mul_f32_e32 v119, 0xbfb8aa3b, v113
	v_mul_f32_e32 v120, 0xbfb8aa3b, v109
	v_exp_f32_e32 v114, v114
	v_exp_f32_e32 v119, v119
	v_exp_f32_e32 v121, v120
	v_rcp_f32_e32 v120, v117
	v_add_f32_e32 v114, 1.0, v114
	v_add_f32_e32 v117, 1.0, v119
	v_add_f32_e32 v119, 1.0, v121
	v_rcp_f32_e32 v114, v114
	v_rcp_f32_e32 v115, v115
	v_rcp_f32_e32 v116, v116
	v_rcp_f32_e32 v117, v117
	v_rcp_f32_e32 v121, v119
	v_rcp_f32_e32 v119, v124
	v_pk_mul_f32 v[114:115], v[110:111], v[114:115]
	v_pk_mul_f32 v[116:117], v[112:113], v[116:117]
	v_pk_mul_f32 v[120:121], v[108:109], v[120:121]
	v_pk_mul_f32 v[118:119], v[106:107], v[118:119]
	v_mov_b32_e32 v124, v150
	v_or_b32_e32 v106, 16, v161
	v_mad_i64_i32 v[106:107], s[72:73], s70, v106, 0
	v_lshl_add_u64 v[106:107], v[106:107], 1, v[122:123]
	v_cvt_pk_bf16_f32 v108, v114, v115
	v_cvt_pk_bf16_f32 v109, v116, v117
	v_cvt_pk_bf16_f32 v110, v118, v119
	v_cvt_pk_bf16_f32 v111, v120, v121
	global_store_dwordx4 v[106:107], v[108:111], off
	s_nop 1
	v_mul_f32_e32 v109, 0xbfb8aa3b, v98
	v_mul_f32_e32 v110, 0xbfb8aa3b, v103
	v_exp_f32_e32 v109, v109
	v_exp_f32_e32 v110, v110
	v_mul_f32_e32 v111, 0xbfb8aa3b, v104
	v_mul_f32_e32 v113, 0xbfb8aa3b, v100
	v_add_f32_e32 v109, 1.0, v109
	v_rcp_f32_e32 v112, v109
	v_add_f32_e32 v109, 1.0, v110
	v_mul_f32_e32 v110, 0xbfb8aa3b, v99
	v_exp_f32_e32 v110, v110
	v_exp_f32_e32 v111, v111
	v_exp_f32_e32 v113, v113
	v_mul_f32_e32 v108, 0xbfb8aa3b, v102
	v_add_f32_e32 v116, 1.0, v110
	v_add_f32_e32 v110, 1.0, v111
	v_add_f32_e32 v111, 1.0, v113
	v_mul_f32_e32 v113, 0xbfb8aa3b, v105
	v_mul_f32_e32 v114, 0xbfb8aa3b, v101
	v_exp_f32_e32 v108, v108
	v_exp_f32_e32 v113, v113
	v_exp_f32_e32 v115, v114
	v_rcp_f32_e32 v114, v111
	v_add_f32_e32 v108, 1.0, v108
	v_add_f32_e32 v111, 1.0, v113
	v_add_f32_e32 v113, 1.0, v115
	v_rcp_f32_e32 v108, v108
	v_rcp_f32_e32 v109, v109
	v_rcp_f32_e32 v110, v110
	v_rcp_f32_e32 v111, v111
	v_rcp_f32_e32 v115, v113
	v_rcp_f32_e32 v113, v116
	v_pk_mul_f32 v[108:109], v[102:103], v[108:109]
	v_pk_mul_f32 v[110:111], v[104:105], v[110:111]
	v_pk_mul_f32 v[114:115], v[100:101], v[114:115]
	v_pk_mul_f32 v[112:113], v[98:99], v[112:113]
	v_mov_b32_e32 v116, v124
	v_cvt_pk_bf16_f32 v98, v108, v109
	v_cvt_pk_bf16_f32 v99, v110, v111
	v_cvt_pk_bf16_f32 v100, v112, v113
	v_cvt_pk_bf16_f32 v101, v114, v115
	global_store_dwordx4 v[106:107], v[98:101], off offset:256
	s_nop 1
	v_mul_f32_e32 v99, 0xbfb8aa3b, v90
	v_mul_f32_e32 v100, 0xbfb8aa3b, v95
	v_exp_f32_e32 v99, v99
	v_exp_f32_e32 v100, v100
	v_mul_f32_e32 v101, 0xbfb8aa3b, v96
	v_mul_f32_e32 v103, 0xbfb8aa3b, v92
	v_add_f32_e32 v99, 1.0, v99
	v_rcp_f32_e32 v102, v99
	v_add_f32_e32 v99, 1.0, v100
	v_mul_f32_e32 v100, 0xbfb8aa3b, v91
	v_exp_f32_e32 v100, v100
	v_exp_f32_e32 v101, v101
	v_exp_f32_e32 v103, v103
	v_mul_f32_e32 v98, 0xbfb8aa3b, v94
	v_add_f32_e32 v106, 1.0, v100
	v_add_f32_e32 v100, 1.0, v101
	v_add_f32_e32 v101, 1.0, v103
	v_mul_f32_e32 v103, 0xbfb8aa3b, v97
	v_mul_f32_e32 v104, 0xbfb8aa3b, v93
	v_exp_f32_e32 v98, v98
	v_exp_f32_e32 v103, v103
	v_exp_f32_e32 v105, v104
	v_rcp_f32_e32 v104, v101
	v_add_f32_e32 v98, 1.0, v98
	v_add_f32_e32 v101, 1.0, v103
	v_add_f32_e32 v103, 1.0, v105
	v_rcp_f32_e32 v98, v98
	v_rcp_f32_e32 v99, v99
	v_rcp_f32_e32 v100, v100
	v_rcp_f32_e32 v101, v101
	v_rcp_f32_e32 v105, v103
	v_rcp_f32_e32 v103, v106
	v_pk_mul_f32 v[98:99], v[94:95], v[98:99]
	v_pk_mul_f32 v[100:101], v[96:97], v[100:101]
	v_pk_mul_f32 v[104:105], v[92:93], v[104:105]
	v_pk_mul_f32 v[102:103], v[90:91], v[102:103]
	v_mov_b32_e32 v106, v116
	v_or_b32_e32 v90, 32, v161
	v_mad_i64_i32 v[90:91], s[72:73], s70, v90, 0
	v_lshl_add_u64 v[90:91], v[90:91], 1, v[122:123]
	v_cvt_pk_bf16_f32 v92, v98, v99
	v_cvt_pk_bf16_f32 v93, v100, v101
	v_cvt_pk_bf16_f32 v94, v102, v103
	v_cvt_pk_bf16_f32 v95, v104, v105
	global_store_dwordx4 v[90:91], v[92:95], off
	s_nop 1
	v_mul_f32_e32 v93, 0xbfb8aa3b, v82
	v_mul_f32_e32 v94, 0xbfb8aa3b, v87
	v_exp_f32_e32 v93, v93
	v_exp_f32_e32 v94, v94
	v_mul_f32_e32 v95, 0xbfb8aa3b, v88
	v_mul_f32_e32 v97, 0xbfb8aa3b, v84
	v_add_f32_e32 v93, 1.0, v93
	v_rcp_f32_e32 v96, v93
	v_add_f32_e32 v93, 1.0, v94
	v_mul_f32_e32 v94, 0xbfb8aa3b, v83
	v_exp_f32_e32 v94, v94
	v_exp_f32_e32 v95, v95
	v_exp_f32_e32 v97, v97
	v_mul_f32_e32 v92, 0xbfb8aa3b, v86
	v_add_f32_e32 v100, 1.0, v94
	v_add_f32_e32 v94, 1.0, v95
	v_add_f32_e32 v95, 1.0, v97
	v_mul_f32_e32 v97, 0xbfb8aa3b, v89
	v_mul_f32_e32 v98, 0xbfb8aa3b, v85
	v_exp_f32_e32 v92, v92
	v_exp_f32_e32 v97, v97
	v_exp_f32_e32 v99, v98
	v_rcp_f32_e32 v98, v95
	v_add_f32_e32 v92, 1.0, v92
	v_add_f32_e32 v95, 1.0, v97
	v_add_f32_e32 v97, 1.0, v99
	v_rcp_f32_e32 v92, v92
	v_rcp_f32_e32 v93, v93
	v_rcp_f32_e32 v94, v94
	v_rcp_f32_e32 v95, v95
	v_rcp_f32_e32 v99, v97
	v_rcp_f32_e32 v97, v100
	v_pk_mul_f32 v[92:93], v[86:87], v[92:93]
	v_pk_mul_f32 v[94:95], v[88:89], v[94:95]
	v_pk_mul_f32 v[98:99], v[84:85], v[98:99]
	v_pk_mul_f32 v[96:97], v[82:83], v[96:97]
	v_mov_b32_e32 v100, v106
	v_cvt_pk_bf16_f32 v82, v92, v93
	v_cvt_pk_bf16_f32 v83, v94, v95
	v_cvt_pk_bf16_f32 v84, v96, v97
	v_cvt_pk_bf16_f32 v85, v98, v99
	global_store_dwordx4 v[90:91], v[82:85], off offset:256
	s_nop 1
	v_mul_f32_e32 v83, 0xbfb8aa3b, v74
	v_mul_f32_e32 v84, 0xbfb8aa3b, v79
	v_exp_f32_e32 v83, v83
	v_exp_f32_e32 v84, v84
	v_mul_f32_e32 v85, 0xbfb8aa3b, v80
	v_mul_f32_e32 v87, 0xbfb8aa3b, v76
	v_add_f32_e32 v83, 1.0, v83
	v_rcp_f32_e32 v86, v83
	v_add_f32_e32 v83, 1.0, v84
	v_mul_f32_e32 v84, 0xbfb8aa3b, v75
	v_exp_f32_e32 v84, v84
	v_exp_f32_e32 v85, v85
	v_exp_f32_e32 v87, v87
	v_mul_f32_e32 v82, 0xbfb8aa3b, v78
	v_add_f32_e32 v90, 1.0, v84
	v_add_f32_e32 v84, 1.0, v85
	v_add_f32_e32 v85, 1.0, v87
	v_mul_f32_e32 v87, 0xbfb8aa3b, v81
	v_mul_f32_e32 v88, 0xbfb8aa3b, v77
	v_exp_f32_e32 v82, v82
	v_exp_f32_e32 v87, v87
	v_exp_f32_e32 v89, v88
	v_rcp_f32_e32 v88, v85
	v_add_f32_e32 v82, 1.0, v82
	v_add_f32_e32 v85, 1.0, v87
	v_add_f32_e32 v87, 1.0, v89
	v_rcp_f32_e32 v82, v82
	v_rcp_f32_e32 v83, v83
	v_rcp_f32_e32 v84, v84
	v_rcp_f32_e32 v85, v85
	v_rcp_f32_e32 v89, v87
	v_rcp_f32_e32 v87, v90
	v_pk_mul_f32 v[82:83], v[78:79], v[82:83]
	v_pk_mul_f32 v[84:85], v[80:81], v[84:85]
	v_pk_mul_f32 v[88:89], v[76:77], v[88:89]
	v_pk_mul_f32 v[86:87], v[74:75], v[86:87]
	v_mov_b32_e32 v90, v100
	v_or_b32_e32 v74, 48, v161
	v_mad_i64_i32 v[74:75], s[72:73], s70, v74, 0
	v_lshl_add_u64 v[74:75], v[74:75], 1, v[122:123]
	v_cvt_pk_bf16_f32 v76, v82, v83
	v_cvt_pk_bf16_f32 v77, v84, v85
	v_cvt_pk_bf16_f32 v78, v86, v87
	v_cvt_pk_bf16_f32 v79, v88, v89
	global_store_dwordx4 v[74:75], v[76:79], off
	s_nop 1
	v_mul_f32_e32 v77, 0xbfb8aa3b, v66
	v_mul_f32_e32 v78, 0xbfb8aa3b, v71
	v_exp_f32_e32 v77, v77
	v_exp_f32_e32 v78, v78
	v_mul_f32_e32 v79, 0xbfb8aa3b, v72
	v_mul_f32_e32 v81, 0xbfb8aa3b, v68
	v_add_f32_e32 v77, 1.0, v77
	v_rcp_f32_e32 v80, v77
	v_add_f32_e32 v77, 1.0, v78
	v_mul_f32_e32 v78, 0xbfb8aa3b, v67
	v_exp_f32_e32 v78, v78
	v_exp_f32_e32 v79, v79
	v_exp_f32_e32 v81, v81
	v_mul_f32_e32 v76, 0xbfb8aa3b, v70
	v_add_f32_e32 v84, 1.0, v78
	v_add_f32_e32 v78, 1.0, v79
	v_add_f32_e32 v79, 1.0, v81
	v_mul_f32_e32 v81, 0xbfb8aa3b, v73
	v_mul_f32_e32 v82, 0xbfb8aa3b, v69
	v_exp_f32_e32 v76, v76
	v_exp_f32_e32 v81, v81
	v_exp_f32_e32 v83, v82
	v_rcp_f32_e32 v82, v79
	v_add_f32_e32 v76, 1.0, v76
	v_add_f32_e32 v79, 1.0, v81
	v_add_f32_e32 v81, 1.0, v83
	v_rcp_f32_e32 v76, v76
	v_rcp_f32_e32 v77, v77
	v_rcp_f32_e32 v78, v78
	v_rcp_f32_e32 v79, v79
	v_rcp_f32_e32 v83, v81
	v_rcp_f32_e32 v81, v84
	v_pk_mul_f32 v[76:77], v[70:71], v[76:77]
	v_pk_mul_f32 v[78:79], v[72:73], v[78:79]
	v_pk_mul_f32 v[82:83], v[68:69], v[82:83]
	v_pk_mul_f32 v[80:81], v[66:67], v[80:81]
	v_mov_b32_e32 v84, v90
	v_cvt_pk_bf16_f32 v66, v76, v77
	v_cvt_pk_bf16_f32 v67, v78, v79
	v_cvt_pk_bf16_f32 v68, v80, v81
	v_cvt_pk_bf16_f32 v69, v82, v83
	global_store_dwordx4 v[74:75], v[66:69], off offset:256
	s_nop 1
	v_mul_f32_e32 v67, 0xbfb8aa3b, v58
	v_mul_f32_e32 v68, 0xbfb8aa3b, v63
	v_exp_f32_e32 v67, v67
	v_exp_f32_e32 v68, v68
	v_mul_f32_e32 v69, 0xbfb8aa3b, v64
	v_mul_f32_e32 v71, 0xbfb8aa3b, v60
	v_add_f32_e32 v67, 1.0, v67
	v_rcp_f32_e32 v70, v67
	v_add_f32_e32 v67, 1.0, v68
	v_mul_f32_e32 v68, 0xbfb8aa3b, v59
	v_exp_f32_e32 v68, v68
	v_exp_f32_e32 v69, v69
	v_exp_f32_e32 v71, v71
	v_mul_f32_e32 v66, 0xbfb8aa3b, v62
	v_add_f32_e32 v74, 1.0, v68
	v_add_f32_e32 v68, 1.0, v69
	v_add_f32_e32 v69, 1.0, v71
	v_mul_f32_e32 v71, 0xbfb8aa3b, v65
	v_mul_f32_e32 v72, 0xbfb8aa3b, v61
	v_exp_f32_e32 v66, v66
	v_exp_f32_e32 v71, v71
	v_exp_f32_e32 v73, v72
	v_rcp_f32_e32 v72, v69
	v_add_f32_e32 v66, 1.0, v66
	v_add_f32_e32 v69, 1.0, v71
	v_add_f32_e32 v71, 1.0, v73
	v_rcp_f32_e32 v66, v66
	v_rcp_f32_e32 v67, v67
	v_rcp_f32_e32 v68, v68
	v_rcp_f32_e32 v69, v69
	v_rcp_f32_e32 v73, v71
	v_rcp_f32_e32 v71, v74
	v_pk_mul_f32 v[66:67], v[62:63], v[66:67]
	v_pk_mul_f32 v[68:69], v[64:65], v[68:69]
	v_pk_mul_f32 v[72:73], v[60:61], v[72:73]
	v_pk_mul_f32 v[70:71], v[58:59], v[70:71]
	v_mov_b32_e32 v74, v84
	v_add_u32_e32 v58, 0x80, v161
	v_mad_i64_i32 v[58:59], s[72:73], s70, v58, 0
	v_lshl_add_u64 v[58:59], v[58:59], 1, v[122:123]
	v_cvt_pk_bf16_f32 v60, v66, v67
	v_cvt_pk_bf16_f32 v61, v68, v69
	v_cvt_pk_bf16_f32 v62, v70, v71
	v_cvt_pk_bf16_f32 v63, v72, v73
	global_store_dwordx4 v[58:59], v[60:63], off
	s_nop 1
	v_mul_f32_e32 v61, 0xbfb8aa3b, v50
	v_mul_f32_e32 v62, 0xbfb8aa3b, v55
	v_exp_f32_e32 v61, v61
	v_exp_f32_e32 v62, v62
	v_mul_f32_e32 v63, 0xbfb8aa3b, v56
	v_mul_f32_e32 v65, 0xbfb8aa3b, v52
	v_add_f32_e32 v61, 1.0, v61
	v_rcp_f32_e32 v64, v61
	v_add_f32_e32 v61, 1.0, v62
	v_mul_f32_e32 v62, 0xbfb8aa3b, v51
	v_exp_f32_e32 v62, v62
	v_exp_f32_e32 v63, v63
	v_exp_f32_e32 v65, v65
	v_mul_f32_e32 v60, 0xbfb8aa3b, v54
	v_add_f32_e32 v68, 1.0, v62
	v_add_f32_e32 v62, 1.0, v63
	v_add_f32_e32 v63, 1.0, v65
	v_mul_f32_e32 v65, 0xbfb8aa3b, v57
	v_mul_f32_e32 v66, 0xbfb8aa3b, v53
	v_exp_f32_e32 v60, v60
	v_exp_f32_e32 v65, v65
	v_exp_f32_e32 v67, v66
	v_rcp_f32_e32 v66, v63
	v_add_f32_e32 v60, 1.0, v60
	v_add_f32_e32 v63, 1.0, v65
	v_add_f32_e32 v65, 1.0, v67
	v_rcp_f32_e32 v60, v60
	v_rcp_f32_e32 v61, v61
	v_rcp_f32_e32 v62, v62
	v_rcp_f32_e32 v63, v63
	v_rcp_f32_e32 v67, v65
	v_rcp_f32_e32 v65, v68
	v_pk_mul_f32 v[60:61], v[54:55], v[60:61]
	v_pk_mul_f32 v[62:63], v[56:57], v[62:63]
	v_pk_mul_f32 v[66:67], v[52:53], v[66:67]
	v_pk_mul_f32 v[64:65], v[50:51], v[64:65]
	v_mov_b32_e32 v68, v74
	v_cvt_pk_bf16_f32 v50, v60, v61
	v_cvt_pk_bf16_f32 v51, v62, v63
	v_cvt_pk_bf16_f32 v52, v64, v65
	v_cvt_pk_bf16_f32 v53, v66, v67
	global_store_dwordx4 v[58:59], v[50:53], off offset:256
	s_nop 1
	v_mul_f32_e32 v51, 0xbfb8aa3b, v42
	v_mul_f32_e32 v52, 0xbfb8aa3b, v47
	v_exp_f32_e32 v51, v51
	v_exp_f32_e32 v52, v52
	v_mul_f32_e32 v53, 0xbfb8aa3b, v48
	v_mul_f32_e32 v55, 0xbfb8aa3b, v44
	v_add_f32_e32 v51, 1.0, v51
	v_rcp_f32_e32 v54, v51
	v_add_f32_e32 v51, 1.0, v52
	v_mul_f32_e32 v52, 0xbfb8aa3b, v43
	v_exp_f32_e32 v52, v52
	v_exp_f32_e32 v53, v53
	v_exp_f32_e32 v55, v55
	v_mul_f32_e32 v50, 0xbfb8aa3b, v46
	v_add_f32_e32 v58, 1.0, v52
	v_add_f32_e32 v52, 1.0, v53
	v_add_f32_e32 v53, 1.0, v55
	v_mul_f32_e32 v55, 0xbfb8aa3b, v49
	v_mul_f32_e32 v56, 0xbfb8aa3b, v45
	v_exp_f32_e32 v50, v50
	v_exp_f32_e32 v55, v55
	v_exp_f32_e32 v57, v56
	v_rcp_f32_e32 v56, v53
	v_add_f32_e32 v50, 1.0, v50
	v_add_f32_e32 v53, 1.0, v55
	v_add_f32_e32 v55, 1.0, v57
	v_rcp_f32_e32 v50, v50
	v_rcp_f32_e32 v51, v51
	v_rcp_f32_e32 v52, v52
	v_rcp_f32_e32 v53, v53
	v_rcp_f32_e32 v57, v55
	v_rcp_f32_e32 v55, v58
	v_pk_mul_f32 v[50:51], v[46:47], v[50:51]
	v_pk_mul_f32 v[52:53], v[48:49], v[52:53]
	v_pk_mul_f32 v[56:57], v[44:45], v[56:57]
	v_pk_mul_f32 v[54:55], v[42:43], v[54:55]
	v_mov_b32_e32 v58, v68
	v_add_u32_e32 v42, 0x90, v161
	v_mad_i64_i32 v[42:43], s[72:73], s70, v42, 0
	v_lshl_add_u64 v[42:43], v[42:43], 1, v[122:123]
	v_cvt_pk_bf16_f32 v44, v50, v51
	v_cvt_pk_bf16_f32 v45, v52, v53
	v_cvt_pk_bf16_f32 v46, v54, v55
	v_cvt_pk_bf16_f32 v47, v56, v57
	global_store_dwordx4 v[42:43], v[44:47], off
	s_nop 1
	v_mul_f32_e32 v45, 0xbfb8aa3b, v34
	v_mul_f32_e32 v46, 0xbfb8aa3b, v39
	v_exp_f32_e32 v45, v45
	v_exp_f32_e32 v46, v46
	v_mul_f32_e32 v47, 0xbfb8aa3b, v40
	v_mul_f32_e32 v49, 0xbfb8aa3b, v36
	v_add_f32_e32 v45, 1.0, v45
	v_rcp_f32_e32 v48, v45
	v_add_f32_e32 v45, 1.0, v46
	v_mul_f32_e32 v46, 0xbfb8aa3b, v35
	v_exp_f32_e32 v46, v46
	v_exp_f32_e32 v47, v47
	v_exp_f32_e32 v49, v49
	v_mul_f32_e32 v44, 0xbfb8aa3b, v38
	v_add_f32_e32 v52, 1.0, v46
	v_add_f32_e32 v46, 1.0, v47
	v_add_f32_e32 v47, 1.0, v49
	v_mul_f32_e32 v49, 0xbfb8aa3b, v41
	v_mul_f32_e32 v50, 0xbfb8aa3b, v37
	v_exp_f32_e32 v44, v44
	v_exp_f32_e32 v49, v49
	v_exp_f32_e32 v51, v50
	v_rcp_f32_e32 v50, v47
	v_add_f32_e32 v44, 1.0, v44
	v_add_f32_e32 v47, 1.0, v49
	v_add_f32_e32 v49, 1.0, v51
	v_rcp_f32_e32 v44, v44
	v_rcp_f32_e32 v45, v45
	v_rcp_f32_e32 v46, v46
	v_rcp_f32_e32 v47, v47
	v_rcp_f32_e32 v51, v49
	v_rcp_f32_e32 v49, v52
	v_pk_mul_f32 v[44:45], v[38:39], v[44:45]
	v_pk_mul_f32 v[46:47], v[40:41], v[46:47]
	v_pk_mul_f32 v[50:51], v[36:37], v[50:51]
	v_pk_mul_f32 v[48:49], v[34:35], v[48:49]
	v_mov_b32_e32 v52, v58
	v_cvt_pk_bf16_f32 v34, v44, v45
	v_cvt_pk_bf16_f32 v35, v46, v47
	v_cvt_pk_bf16_f32 v36, v48, v49
	v_cvt_pk_bf16_f32 v37, v50, v51
	global_store_dwordx4 v[42:43], v[34:37], off offset:256
	s_nop 1
	v_mul_f32_e32 v35, 0xbfb8aa3b, v26
	v_mul_f32_e32 v36, 0xbfb8aa3b, v31
	v_exp_f32_e32 v35, v35
	v_exp_f32_e32 v36, v36
	v_mul_f32_e32 v37, 0xbfb8aa3b, v32
	v_mul_f32_e32 v39, 0xbfb8aa3b, v28
	v_add_f32_e32 v35, 1.0, v35
	v_rcp_f32_e32 v38, v35
	v_add_f32_e32 v35, 1.0, v36
	v_mul_f32_e32 v36, 0xbfb8aa3b, v27
	v_exp_f32_e32 v36, v36
	v_exp_f32_e32 v37, v37
	v_exp_f32_e32 v39, v39
	v_mul_f32_e32 v34, 0xbfb8aa3b, v30
	v_add_f32_e32 v42, 1.0, v36
	v_add_f32_e32 v36, 1.0, v37
	v_add_f32_e32 v37, 1.0, v39
	v_mul_f32_e32 v39, 0xbfb8aa3b, v33
	v_mul_f32_e32 v40, 0xbfb8aa3b, v29
	v_exp_f32_e32 v34, v34
	v_exp_f32_e32 v39, v39
	v_exp_f32_e32 v41, v40
	v_rcp_f32_e32 v40, v37
	v_add_f32_e32 v34, 1.0, v34
	v_add_f32_e32 v37, 1.0, v39
	v_add_f32_e32 v39, 1.0, v41
	v_rcp_f32_e32 v34, v34
	v_rcp_f32_e32 v35, v35
	v_rcp_f32_e32 v36, v36
	v_rcp_f32_e32 v37, v37
	v_rcp_f32_e32 v41, v39
	v_rcp_f32_e32 v39, v42
	v_pk_mul_f32 v[34:35], v[30:31], v[34:35]
	v_pk_mul_f32 v[36:37], v[32:33], v[36:37]
	v_pk_mul_f32 v[40:41], v[28:29], v[40:41]
	v_pk_mul_f32 v[38:39], v[26:27], v[38:39]
	v_mov_b32_e32 v42, v52
	v_add_u32_e32 v26, 0xa0, v161
	v_mad_i64_i32 v[26:27], s[72:73], s70, v26, 0
	v_lshl_add_u64 v[26:27], v[26:27], 1, v[122:123]
	v_cvt_pk_bf16_f32 v28, v34, v35
	v_cvt_pk_bf16_f32 v29, v36, v37
	v_cvt_pk_bf16_f32 v30, v38, v39
	v_cvt_pk_bf16_f32 v31, v40, v41
	global_store_dwordx4 v[26:27], v[28:31], off
	s_nop 1
	v_mul_f32_e32 v29, 0xbfb8aa3b, v18
	v_mul_f32_e32 v30, 0xbfb8aa3b, v23
	v_exp_f32_e32 v29, v29
	v_exp_f32_e32 v30, v30
	v_mul_f32_e32 v31, 0xbfb8aa3b, v24
	v_mul_f32_e32 v33, 0xbfb8aa3b, v20
	v_add_f32_e32 v29, 1.0, v29
	v_rcp_f32_e32 v32, v29
	v_add_f32_e32 v29, 1.0, v30
	v_mul_f32_e32 v30, 0xbfb8aa3b, v19
	v_exp_f32_e32 v30, v30
	v_exp_f32_e32 v31, v31
	v_exp_f32_e32 v33, v33
	v_mul_f32_e32 v28, 0xbfb8aa3b, v22
	v_add_f32_e32 v36, 1.0, v30
	v_add_f32_e32 v30, 1.0, v31
	v_add_f32_e32 v31, 1.0, v33
	v_mul_f32_e32 v33, 0xbfb8aa3b, v25
	v_mul_f32_e32 v34, 0xbfb8aa3b, v21
	v_exp_f32_e32 v28, v28
	v_exp_f32_e32 v33, v33
	v_exp_f32_e32 v35, v34
	v_rcp_f32_e32 v34, v31
	v_add_f32_e32 v28, 1.0, v28
	v_add_f32_e32 v31, 1.0, v33
	v_add_f32_e32 v33, 1.0, v35
	v_rcp_f32_e32 v28, v28
	v_rcp_f32_e32 v29, v29
	v_rcp_f32_e32 v30, v30
	v_rcp_f32_e32 v31, v31
	v_rcp_f32_e32 v35, v33
	v_rcp_f32_e32 v33, v36
	v_pk_mul_f32 v[28:29], v[22:23], v[28:29]
	v_pk_mul_f32 v[30:31], v[24:25], v[30:31]
	v_pk_mul_f32 v[34:35], v[20:21], v[34:35]
	v_pk_mul_f32 v[32:33], v[18:19], v[32:33]
	v_mov_b32_e32 v36, v42
	v_cvt_pk_bf16_f32 v18, v28, v29
	v_cvt_pk_bf16_f32 v19, v30, v31
	v_cvt_pk_bf16_f32 v20, v32, v33
	v_cvt_pk_bf16_f32 v21, v34, v35
	s_mov_b64 s[72:73], -1
	global_store_dwordx4 v[26:27], v[18:21], off offset:256
	s_nop 1
	v_mul_f32_e32 v19, 0xbfb8aa3b, v10
	v_mul_f32_e32 v20, 0xbfb8aa3b, v15
	v_exp_f32_e32 v19, v19
	v_exp_f32_e32 v20, v20
	v_mul_f32_e32 v21, 0xbfb8aa3b, v16
	v_mul_f32_e32 v23, 0xbfb8aa3b, v12
	v_add_f32_e32 v19, 1.0, v19
	v_rcp_f32_e32 v22, v19
	v_add_f32_e32 v19, 1.0, v20
	v_mul_f32_e32 v20, 0xbfb8aa3b, v11
	v_exp_f32_e32 v20, v20
	v_exp_f32_e32 v21, v21
	v_exp_f32_e32 v23, v23
	v_mul_f32_e32 v18, 0xbfb8aa3b, v14
	v_add_f32_e32 v26, 1.0, v20
	v_add_f32_e32 v20, 1.0, v21
	v_add_f32_e32 v21, 1.0, v23
	v_mul_f32_e32 v23, 0xbfb8aa3b, v17
	v_mul_f32_e32 v24, 0xbfb8aa3b, v13
	v_exp_f32_e32 v18, v18
	v_exp_f32_e32 v23, v23
	v_exp_f32_e32 v25, v24
	v_rcp_f32_e32 v24, v21
	v_add_f32_e32 v18, 1.0, v18
	v_add_f32_e32 v21, 1.0, v23
	v_add_f32_e32 v23, 1.0, v25
	v_rcp_f32_e32 v18, v18
	v_rcp_f32_e32 v19, v19
	v_rcp_f32_e32 v20, v20
	v_rcp_f32_e32 v21, v21
	v_rcp_f32_e32 v25, v23
	v_rcp_f32_e32 v23, v26
	v_pk_mul_f32 v[18:19], v[14:15], v[18:19]
	v_pk_mul_f32 v[20:21], v[16:17], v[20:21]
	v_pk_mul_f32 v[24:25], v[12:13], v[24:25]
	v_pk_mul_f32 v[22:23], v[10:11], v[22:23]
	v_mov_b32_e32 v26, v36
	v_add_u32_e32 v10, 0xb0, v161
	v_mad_i64_i32 v[10:11], s[70:71], s70, v10, 0
	v_lshl_add_u64 v[10:11], v[10:11], 1, v[122:123]
	v_cvt_pk_bf16_f32 v12, v18, v19
	v_cvt_pk_bf16_f32 v13, v20, v21
	v_cvt_pk_bf16_f32 v14, v22, v23
	v_cvt_pk_bf16_f32 v15, v24, v25
	s_mov_b64 s[8:9], -1
	global_store_dwordx4 v[10:11], v[12:15], off
	s_nop 1
	v_mul_f32_e32 v13, 0xbfb8aa3b, v2
	v_mul_f32_e32 v14, 0xbfb8aa3b, v7
	v_exp_f32_e32 v13, v13
	v_exp_f32_e32 v14, v14
	v_mul_f32_e32 v15, 0xbfb8aa3b, v8
	v_mul_f32_e32 v17, 0xbfb8aa3b, v4
	v_add_f32_e32 v13, 1.0, v13
	v_rcp_f32_e32 v16, v13
	v_add_f32_e32 v13, 1.0, v14
	v_mul_f32_e32 v14, 0xbfb8aa3b, v3
	v_exp_f32_e32 v14, v14
	v_exp_f32_e32 v15, v15
	v_exp_f32_e32 v17, v17
	v_mul_f32_e32 v12, 0xbfb8aa3b, v6
	v_add_f32_e32 v20, 1.0, v14
	v_add_f32_e32 v14, 1.0, v15
	v_add_f32_e32 v15, 1.0, v17
	v_mul_f32_e32 v17, 0xbfb8aa3b, v9
	v_mul_f32_e32 v18, 0xbfb8aa3b, v5
	v_exp_f32_e32 v12, v12
	v_exp_f32_e32 v17, v17
	v_exp_f32_e32 v19, v18
	v_rcp_f32_e32 v18, v15
	v_add_f32_e32 v12, 1.0, v12
	v_add_f32_e32 v15, 1.0, v17
	v_add_f32_e32 v17, 1.0, v19
	v_rcp_f32_e32 v12, v12
	v_rcp_f32_e32 v13, v13
	v_rcp_f32_e32 v14, v14
	v_rcp_f32_e32 v15, v15
	v_rcp_f32_e32 v19, v17
	v_rcp_f32_e32 v17, v20
	v_pk_mul_f32 v[12:13], v[6:7], v[12:13]
	v_pk_mul_f32 v[14:15], v[8:9], v[14:15]
	v_pk_mul_f32 v[18:19], v[4:5], v[18:19]
	v_pk_mul_f32 v[16:17], v[2:3], v[16:17]
	v_mov_b32_e32 v20, v26
	s_and_b64 vcc, exec, s[54:55]
	v_cvt_pk_bf16_f32 v2, v12, v13
	v_cvt_pk_bf16_f32 v3, v14, v15
	v_cvt_pk_bf16_f32 v4, v16, v17
	v_cvt_pk_bf16_f32 v5, v18, v19
	global_store_dwordx4 v[10:11], v[2:5], off offset:256
	s_branch .LBB0_416
.Lmy_e1_act2:
	s_xor_b64 s[74:75], s[74:75], -1
	s_xor_b64 s[76:77], s[76:77], -1
	v_mul_f32_e32 v147, 0xbfb8aa3b, v122
	v_exp_f32_e32 v147, v147
	v_mul_f32_e32 v148, 0xbfb8aa3b, v127
	v_mul_f32_e32 v149, 0xbfb8aa3b, v123
	v_exp_f32_e32 v148, v148
	v_exp_f32_e32 v149, v149
	v_add_f32_e32 v147, 1.0, v147
	v_rcp_f32_e32 v150, v147
	v_add_f32_e32 v147, 1.0, v148
	v_add_f32_e32 v148, 1.0, v149
	v_mul_f32_e32 v149, 0xbfb8aa3b, v128
	v_mul_f32_e32 v151, 0xbfb8aa3b, v124
	v_exp_f32_e32 v149, v149
	v_exp_f32_e32 v152, v151
	v_rcp_f32_e32 v151, v148
	v_mul_f32_e32 v146, 0xbfb8aa3b, v126
	v_add_f32_e32 v148, 1.0, v149
	v_add_f32_e32 v149, 1.0, v152
	v_mul_f32_e32 v152, 0xbfb8aa3b, v129
	v_exp_f32_e32 v153, v152
	v_mul_f32_e32 v152, 0xbfb8aa3b, v125
	v_exp_f32_e32 v146, v146
	v_exp_f32_e32 v161, v152
	v_rcp_f32_e32 v152, v149
	v_add_f32_e32 v149, 1.0, v153
	v_add_f32_e32 v146, 1.0, v146
	v_add_f32_e32 v153, 1.0, v161
	v_rcp_f32_e32 v146, v146
	v_rcp_f32_e32 v147, v147
	v_rcp_f32_e32 v148, v148
	v_rcp_f32_e32 v149, v149
	v_rcp_f32_e32 v153, v153
	v_mov_b32_e32 v162, 0
	s_mov_b64 s[78:79], 0
	s_lshl_b32 s6, s6, 8
	s_add_i32 s6, s7, s6
	v_or_b32_e32 v122, s6, v156
	s_lshl_b32 s6, s72, 1
	s_add_u32 s6, s38, s6
	v_lshl_add_u32 v161, s8, 8, v154
	s_addc_u32 s7, s39, 0
	v_ashrrev_i32_e32 v123, 31, v122
	v_lshl_add_u64 v[122:123], v[122:123], 1, s[6:7]
	v_mad_i64_i32 v[124:125], s[6:7], s70, v161, 0
	v_lshl_add_u64 v[124:125], v[124:125], 1, v[122:123]
	v_cvt_pk_bf16_f32 v126, v146, v147
	v_cvt_pk_bf16_f32 v127, v148, v149
	v_cvt_pk_bf16_f32 v128, v150, v151
	v_cvt_pk_bf16_f32 v129, v152, v153
	global_store_dwordx4 v[124:125], v[126:129], off
	s_nop 1
	v_mul_f32_e32 v127, 0xbfb8aa3b, v114
	v_exp_f32_e32 v127, v127
	v_mul_f32_e32 v128, 0xbfb8aa3b, v119
	v_mul_f32_e32 v129, 0xbfb8aa3b, v115
	v_exp_f32_e32 v128, v128
	v_exp_f32_e32 v129, v129
	v_add_f32_e32 v127, 1.0, v127
	v_rcp_f32_e32 v146, v127
	v_add_f32_e32 v127, 1.0, v128
	v_add_f32_e32 v128, 1.0, v129
	v_mul_f32_e32 v129, 0xbfb8aa3b, v120
	v_mul_f32_e32 v147, 0xbfb8aa3b, v116
	v_exp_f32_e32 v129, v129
	v_exp_f32_e32 v148, v147
	v_rcp_f32_e32 v147, v128
	v_mul_f32_e32 v126, 0xbfb8aa3b, v118
	v_add_f32_e32 v128, 1.0, v129
	v_add_f32_e32 v129, 1.0, v148
	v_mul_f32_e32 v148, 0xbfb8aa3b, v121
	v_exp_f32_e32 v149, v148
	v_mul_f32_e32 v148, 0xbfb8aa3b, v117
	v_exp_f32_e32 v126, v126
	v_exp_f32_e32 v150, v148
	v_rcp_f32_e32 v148, v129
	v_add_f32_e32 v129, 1.0, v149
	v_add_f32_e32 v126, 1.0, v126
	v_add_f32_e32 v149, 1.0, v150
	v_rcp_f32_e32 v126, v126
	v_rcp_f32_e32 v127, v127
	v_rcp_f32_e32 v128, v128
	v_rcp_f32_e32 v129, v129
	v_rcp_f32_e32 v149, v149
	v_mov_b32_e32 v150, v162
	v_cvt_pk_bf16_f32 v114, v126, v127
	v_cvt_pk_bf16_f32 v115, v128, v129
	v_cvt_pk_bf16_f32 v116, v146, v147
	v_cvt_pk_bf16_f32 v117, v148, v149
	global_store_dwordx4 v[124:125], v[114:117], off offset:256
	s_nop 1
	v_mul_f32_e32 v115, 0xbfb8aa3b, v106
	v_exp_f32_e32 v115, v115
	v_mul_f32_e32 v116, 0xbfb8aa3b, v111
	v_mul_f32_e32 v117, 0xbfb8aa3b, v107
	v_exp_f32_e32 v116, v116
	v_exp_f32_e32 v117, v117
	v_add_f32_e32 v115, 1.0, v115
	v_rcp_f32_e32 v118, v115
	v_add_f32_e32 v115, 1.0, v116
	v_add_f32_e32 v116, 1.0, v117
	v_mul_f32_e32 v117, 0xbfb8aa3b, v112
	v_mul_f32_e32 v119, 0xbfb8aa3b, v108
	v_exp_f32_e32 v117, v117
	v_exp_f32_e32 v120, v119
	v_rcp_f32_e32 v119, v116
	v_mul_f32_e32 v114, 0xbfb8aa3b, v110
	v_add_f32_e32 v116, 1.0, v117
	v_add_f32_e32 v117, 1.0, v120
	v_mul_f32_e32 v120, 0xbfb8aa3b, v113
	v_exp_f32_e32 v121, v120
	v_mul_f32_e32 v120, 0xbfb8aa3b, v109
	v_exp_f32_e32 v114, v114
	v_exp_f32_e32 v124, v120
	v_rcp_f32_e32 v120, v117
	v_add_f32_e32 v117, 1.0, v121
	v_add_f32_e32 v114, 1.0, v114
	v_add_f32_e32 v121, 1.0, v124
	v_rcp_f32_e32 v114, v114
	v_rcp_f32_e32 v115, v115
	v_rcp_f32_e32 v116, v116
	v_rcp_f32_e32 v117, v117
	v_rcp_f32_e32 v121, v121
	v_mov_b32_e32 v124, v150
	v_or_b32_e32 v106, 16, v161
	v_mad_i64_i32 v[106:107], s[72:73], s70, v106, 0
	v_lshl_add_u64 v[106:107], v[106:107], 1, v[122:123]
	v_cvt_pk_bf16_f32 v108, v114, v115
	v_cvt_pk_bf16_f32 v109, v116, v117
	v_cvt_pk_bf16_f32 v110, v118, v119
	v_cvt_pk_bf16_f32 v111, v120, v121
	global_store_dwordx4 v[106:107], v[108:111], off
	s_nop 1
	v_mul_f32_e32 v109, 0xbfb8aa3b, v98
	v_exp_f32_e32 v109, v109
	v_mul_f32_e32 v110, 0xbfb8aa3b, v103
	v_mul_f32_e32 v111, 0xbfb8aa3b, v99
	v_exp_f32_e32 v110, v110
	v_exp_f32_e32 v111, v111
	v_add_f32_e32 v109, 1.0, v109
	v_rcp_f32_e32 v112, v109
	v_add_f32_e32 v109, 1.0, v110
	v_add_f32_e32 v110, 1.0, v111
	v_mul_f32_e32 v111, 0xbfb8aa3b, v104
	v_mul_f32_e32 v113, 0xbfb8aa3b, v100
	v_exp_f32_e32 v111, v111
	v_exp_f32_e32 v114, v113
	v_rcp_f32_e32 v113, v110
	v_mul_f32_e32 v108, 0xbfb8aa3b, v102
	v_add_f32_e32 v110, 1.0, v111
	v_add_f32_e32 v111, 1.0, v114
	v_mul_f32_e32 v114, 0xbfb8aa3b, v105
	v_exp_f32_e32 v115, v114
	v_mul_f32_e32 v114, 0xbfb8aa3b, v101
	v_exp_f32_e32 v108, v108
	v_exp_f32_e32 v116, v114
	v_rcp_f32_e32 v114, v111
	v_add_f32_e32 v111, 1.0, v115
	v_add_f32_e32 v108, 1.0, v108
	v_add_f32_e32 v115, 1.0, v116
	v_rcp_f32_e32 v108, v108
	v_rcp_f32_e32 v109, v109
	v_rcp_f32_e32 v110, v110
	v_rcp_f32_e32 v111, v111
	v_rcp_f32_e32 v115, v115
	v_mov_b32_e32 v116, v124
	v_cvt_pk_bf16_f32 v98, v108, v109
	v_cvt_pk_bf16_f32 v99, v110, v111
	v_cvt_pk_bf16_f32 v100, v112, v113
	v_cvt_pk_bf16_f32 v101, v114, v115
	global_store_dwordx4 v[106:107], v[98:101], off offset:256
	s_nop 1
	v_mul_f32_e32 v99, 0xbfb8aa3b, v90
	v_exp_f32_e32 v99, v99
	v_mul_f32_e32 v100, 0xbfb8aa3b, v95
	v_mul_f32_e32 v101, 0xbfb8aa3b, v91
	v_exp_f32_e32 v100, v100
	v_exp_f32_e32 v101, v101
	v_add_f32_e32 v99, 1.0, v99
	v_rcp_f32_e32 v102, v99
	v_add_f32_e32 v99, 1.0, v100
	v_add_f32_e32 v100, 1.0, v101
	v_mul_f32_e32 v101, 0xbfb8aa3b, v96
	v_mul_f32_e32 v103, 0xbfb8aa3b, v92
	v_exp_f32_e32 v101, v101
	v_exp_f32_e32 v104, v103
	v_rcp_f32_e32 v103, v100
	v_mul_f32_e32 v98, 0xbfb8aa3b, v94
	v_add_f32_e32 v100, 1.0, v101
	v_add_f32_e32 v101, 1.0, v104
	v_mul_f32_e32 v104, 0xbfb8aa3b, v97
	v_exp_f32_e32 v105, v104
	v_mul_f32_e32 v104, 0xbfb8aa3b, v93
	v_exp_f32_e32 v98, v98
	v_exp_f32_e32 v106, v104
	v_rcp_f32_e32 v104, v101
	v_add_f32_e32 v101, 1.0, v105
	v_add_f32_e32 v98, 1.0, v98
	v_add_f32_e32 v105, 1.0, v106
	v_rcp_f32_e32 v98, v98
	v_rcp_f32_e32 v99, v99
	v_rcp_f32_e32 v100, v100
	v_rcp_f32_e32 v101, v101
	v_rcp_f32_e32 v105, v105
	v_mov_b32_e32 v106, v116
	v_or_b32_e32 v90, 32, v161
	v_mad_i64_i32 v[90:91], s[72:73], s70, v90, 0
	v_lshl_add_u64 v[90:91], v[90:91], 1, v[122:123]
	v_cvt_pk_bf16_f32 v92, v98, v99
	v_cvt_pk_bf16_f32 v93, v100, v101
	v_cvt_pk_bf16_f32 v94, v102, v103
	v_cvt_pk_bf16_f32 v95, v104, v105
	global_store_dwordx4 v[90:91], v[92:95], off
	s_nop 1
	v_mul_f32_e32 v93, 0xbfb8aa3b, v82
	v_exp_f32_e32 v93, v93
	v_mul_f32_e32 v94, 0xbfb8aa3b, v87
	v_mul_f32_e32 v95, 0xbfb8aa3b, v83
	v_exp_f32_e32 v94, v94
	v_exp_f32_e32 v95, v95
	v_add_f32_e32 v93, 1.0, v93
	v_rcp_f32_e32 v96, v93
	v_add_f32_e32 v93, 1.0, v94
	v_add_f32_e32 v94, 1.0, v95
	v_mul_f32_e32 v95, 0xbfb8aa3b, v88
	v_mul_f32_e32 v97, 0xbfb8aa3b, v84
	v_exp_f32_e32 v95, v95
	v_exp_f32_e32 v98, v97
	v_rcp_f32_e32 v97, v94
	v_mul_f32_e32 v92, 0xbfb8aa3b, v86
	v_add_f32_e32 v94, 1.0, v95
	v_add_f32_e32 v95, 1.0, v98
	v_mul_f32_e32 v98, 0xbfb8aa3b, v89
	v_exp_f32_e32 v99, v98
	v_mul_f32_e32 v98, 0xbfb8aa3b, v85
	v_exp_f32_e32 v92, v92
	v_exp_f32_e32 v100, v98
	v_rcp_f32_e32 v98, v95
	v_add_f32_e32 v95, 1.0, v99
	v_add_f32_e32 v92, 1.0, v92
	v_add_f32_e32 v99, 1.0, v100
	v_rcp_f32_e32 v92, v92
	v_rcp_f32_e32 v93, v93
	v_rcp_f32_e32 v94, v94
	v_rcp_f32_e32 v95, v95
	v_rcp_f32_e32 v99, v99
	v_mov_b32_e32 v100, v106
	v_cvt_pk_bf16_f32 v82, v92, v93
	v_cvt_pk_bf16_f32 v83, v94, v95
	v_cvt_pk_bf16_f32 v84, v96, v97
	v_cvt_pk_bf16_f32 v85, v98, v99
	global_store_dwordx4 v[90:91], v[82:85], off offset:256
	s_nop 1
	v_mul_f32_e32 v83, 0xbfb8aa3b, v74
	v_exp_f32_e32 v83, v83
	v_mul_f32_e32 v84, 0xbfb8aa3b, v79
	v_mul_f32_e32 v85, 0xbfb8aa3b, v75
	v_exp_f32_e32 v84, v84
	v_exp_f32_e32 v85, v85
	v_add_f32_e32 v83, 1.0, v83
	v_rcp_f32_e32 v86, v83
	v_add_f32_e32 v83, 1.0, v84
	v_add_f32_e32 v84, 1.0, v85
	v_mul_f32_e32 v85, 0xbfb8aa3b, v80
	v_mul_f32_e32 v87, 0xbfb8aa3b, v76
	v_exp_f32_e32 v85, v85
	v_exp_f32_e32 v88, v87
	v_rcp_f32_e32 v87, v84
	v_mul_f32_e32 v82, 0xbfb8aa3b, v78
	v_add_f32_e32 v84, 1.0, v85
	v_add_f32_e32 v85, 1.0, v88
	v_mul_f32_e32 v88, 0xbfb8aa3b, v81
	v_exp_f32_e32 v89, v88
	v_mul_f32_e32 v88, 0xbfb8aa3b, v77
	v_exp_f32_e32 v82, v82
	v_exp_f32_e32 v90, v88
	v_rcp_f32_e32 v88, v85
	v_add_f32_e32 v85, 1.0, v89
	v_add_f32_e32 v82, 1.0, v82
	v_add_f32_e32 v89, 1.0, v90
	v_rcp_f32_e32 v82, v82
	v_rcp_f32_e32 v83, v83
	v_rcp_f32_e32 v84, v84
	v_rcp_f32_e32 v85, v85
	v_rcp_f32_e32 v89, v89
	v_mov_b32_e32 v90, v100
	v_or_b32_e32 v74, 48, v161
	v_mad_i64_i32 v[74:75], s[72:73], s70, v74, 0
	v_lshl_add_u64 v[74:75], v[74:75], 1, v[122:123]
	v_cvt_pk_bf16_f32 v76, v82, v83
	v_cvt_pk_bf16_f32 v77, v84, v85
	v_cvt_pk_bf16_f32 v78, v86, v87
	v_cvt_pk_bf16_f32 v79, v88, v89
	global_store_dwordx4 v[74:75], v[76:79], off
	s_nop 1
	v_mul_f32_e32 v77, 0xbfb8aa3b, v66
	v_exp_f32_e32 v77, v77
	v_mul_f32_e32 v78, 0xbfb8aa3b, v71
	v_mul_f32_e32 v79, 0xbfb8aa3b, v67
	v_exp_f32_e32 v78, v78
	v_exp_f32_e32 v79, v79
	v_add_f32_e32 v77, 1.0, v77
	v_rcp_f32_e32 v80, v77
	v_add_f32_e32 v77, 1.0, v78
	v_add_f32_e32 v78, 1.0, v79
	v_mul_f32_e32 v79, 0xbfb8aa3b, v72
	v_mul_f32_e32 v81, 0xbfb8aa3b, v68
	v_exp_f32_e32 v79, v79
	v_exp_f32_e32 v82, v81
	v_rcp_f32_e32 v81, v78
	v_mul_f32_e32 v76, 0xbfb8aa3b, v70
	v_add_f32_e32 v78, 1.0, v79
	v_add_f32_e32 v79, 1.0, v82
	v_mul_f32_e32 v82, 0xbfb8aa3b, v73
	v_exp_f32_e32 v83, v82
	v_mul_f32_e32 v82, 0xbfb8aa3b, v69
	v_exp_f32_e32 v76, v76
	v_exp_f32_e32 v84, v82
	v_rcp_f32_e32 v82, v79
	v_add_f32_e32 v79, 1.0, v83
	v_add_f32_e32 v76, 1.0, v76
	v_add_f32_e32 v83, 1.0, v84
	v_rcp_f32_e32 v76, v76
	v_rcp_f32_e32 v77, v77
	v_rcp_f32_e32 v78, v78
	v_rcp_f32_e32 v79, v79
	v_rcp_f32_e32 v83, v83
	v_mov_b32_e32 v84, v90
	v_cvt_pk_bf16_f32 v66, v76, v77
	v_cvt_pk_bf16_f32 v67, v78, v79
	v_cvt_pk_bf16_f32 v68, v80, v81
	v_cvt_pk_bf16_f32 v69, v82, v83
	global_store_dwordx4 v[74:75], v[66:69], off offset:256
	s_nop 1
	v_mul_f32_e32 v67, 0xbfb8aa3b, v58
	v_exp_f32_e32 v67, v67
	v_mul_f32_e32 v68, 0xbfb8aa3b, v63
	v_mul_f32_e32 v69, 0xbfb8aa3b, v59
	v_exp_f32_e32 v68, v68
	v_exp_f32_e32 v69, v69
	v_add_f32_e32 v67, 1.0, v67
	v_rcp_f32_e32 v70, v67
	v_add_f32_e32 v67, 1.0, v68
	v_add_f32_e32 v68, 1.0, v69
	v_mul_f32_e32 v69, 0xbfb8aa3b, v64
	v_mul_f32_e32 v71, 0xbfb8aa3b, v60
	v_exp_f32_e32 v69, v69
	v_exp_f32_e32 v72, v71
	v_rcp_f32_e32 v71, v68
	v_mul_f32_e32 v66, 0xbfb8aa3b, v62
	v_add_f32_e32 v68, 1.0, v69
	v_add_f32_e32 v69, 1.0, v72
	v_mul_f32_e32 v72, 0xbfb8aa3b, v65
	v_exp_f32_e32 v73, v72
	v_mul_f32_e32 v72, 0xbfb8aa3b, v61
	v_exp_f32_e32 v66, v66
	v_exp_f32_e32 v74, v72
	v_rcp_f32_e32 v72, v69
	v_add_f32_e32 v69, 1.0, v73
	v_add_f32_e32 v66, 1.0, v66
	v_add_f32_e32 v73, 1.0, v74
	v_rcp_f32_e32 v66, v66
	v_rcp_f32_e32 v67, v67
	v_rcp_f32_e32 v68, v68
	v_rcp_f32_e32 v69, v69
	v_rcp_f32_e32 v73, v73
	v_mov_b32_e32 v74, v84
	v_add_u32_e32 v58, 0x80, v161
	v_mad_i64_i32 v[58:59], s[72:73], s70, v58, 0
	v_lshl_add_u64 v[58:59], v[58:59], 1, v[122:123]
	v_cvt_pk_bf16_f32 v60, v66, v67
	v_cvt_pk_bf16_f32 v61, v68, v69
	v_cvt_pk_bf16_f32 v62, v70, v71
	v_cvt_pk_bf16_f32 v63, v72, v73
	global_store_dwordx4 v[58:59], v[60:63], off
	s_nop 1
	v_mul_f32_e32 v61, 0xbfb8aa3b, v50
	v_exp_f32_e32 v61, v61
	v_mul_f32_e32 v62, 0xbfb8aa3b, v55
	v_mul_f32_e32 v63, 0xbfb8aa3b, v51
	v_exp_f32_e32 v62, v62
	v_exp_f32_e32 v63, v63
	v_add_f32_e32 v61, 1.0, v61
	v_rcp_f32_e32 v64, v61
	v_add_f32_e32 v61, 1.0, v62
	v_add_f32_e32 v62, 1.0, v63
	v_mul_f32_e32 v63, 0xbfb8aa3b, v56
	v_mul_f32_e32 v65, 0xbfb8aa3b, v52
	v_exp_f32_e32 v63, v63
	v_exp_f32_e32 v66, v65
	v_rcp_f32_e32 v65, v62
	v_mul_f32_e32 v60, 0xbfb8aa3b, v54
	v_add_f32_e32 v62, 1.0, v63
	v_add_f32_e32 v63, 1.0, v66
	v_mul_f32_e32 v66, 0xbfb8aa3b, v57
	v_exp_f32_e32 v67, v66
	v_mul_f32_e32 v66, 0xbfb8aa3b, v53
	v_exp_f32_e32 v60, v60
	v_exp_f32_e32 v68, v66
	v_rcp_f32_e32 v66, v63
	v_add_f32_e32 v63, 1.0, v67
	v_add_f32_e32 v60, 1.0, v60
	v_add_f32_e32 v67, 1.0, v68
	v_rcp_f32_e32 v60, v60
	v_rcp_f32_e32 v61, v61
	v_rcp_f32_e32 v62, v62
	v_rcp_f32_e32 v63, v63
	v_rcp_f32_e32 v67, v67
	v_mov_b32_e32 v68, v74
	v_cvt_pk_bf16_f32 v50, v60, v61
	v_cvt_pk_bf16_f32 v51, v62, v63
	v_cvt_pk_bf16_f32 v52, v64, v65
	v_cvt_pk_bf16_f32 v53, v66, v67
	global_store_dwordx4 v[58:59], v[50:53], off offset:256
	s_nop 1
	v_mul_f32_e32 v51, 0xbfb8aa3b, v42
	v_exp_f32_e32 v51, v51
	v_mul_f32_e32 v52, 0xbfb8aa3b, v47
	v_mul_f32_e32 v53, 0xbfb8aa3b, v43
	v_exp_f32_e32 v52, v52
	v_exp_f32_e32 v53, v53
	v_add_f32_e32 v51, 1.0, v51
	v_rcp_f32_e32 v54, v51
	v_add_f32_e32 v51, 1.0, v52
	v_add_f32_e32 v52, 1.0, v53
	v_mul_f32_e32 v53, 0xbfb8aa3b, v48
	v_mul_f32_e32 v55, 0xbfb8aa3b, v44
	v_exp_f32_e32 v53, v53
	v_exp_f32_e32 v56, v55
	v_rcp_f32_e32 v55, v52
	v_mul_f32_e32 v50, 0xbfb8aa3b, v46
	v_add_f32_e32 v52, 1.0, v53
	v_add_f32_e32 v53, 1.0, v56
	v_mul_f32_e32 v56, 0xbfb8aa3b, v49
	v_exp_f32_e32 v57, v56
	v_mul_f32_e32 v56, 0xbfb8aa3b, v45
	v_exp_f32_e32 v50, v50
	v_exp_f32_e32 v58, v56
	v_rcp_f32_e32 v56, v53
	v_add_f32_e32 v53, 1.0, v57
	v_add_f32_e32 v50, 1.0, v50
	v_add_f32_e32 v57, 1.0, v58
	v_rcp_f32_e32 v50, v50
	v_rcp_f32_e32 v51, v51
	v_rcp_f32_e32 v52, v52
	v_rcp_f32_e32 v53, v53
	v_rcp_f32_e32 v57, v57
	v_mov_b32_e32 v58, v68
	v_add_u32_e32 v42, 0x90, v161
	v_mad_i64_i32 v[42:43], s[72:73], s70, v42, 0
	v_lshl_add_u64 v[42:43], v[42:43], 1, v[122:123]
	v_cvt_pk_bf16_f32 v44, v50, v51
	v_cvt_pk_bf16_f32 v45, v52, v53
	v_cvt_pk_bf16_f32 v46, v54, v55
	v_cvt_pk_bf16_f32 v47, v56, v57
	global_store_dwordx4 v[42:43], v[44:47], off
	s_nop 1
	v_mul_f32_e32 v45, 0xbfb8aa3b, v34
	v_exp_f32_e32 v45, v45
	v_mul_f32_e32 v46, 0xbfb8aa3b, v39
	v_mul_f32_e32 v47, 0xbfb8aa3b, v35
	v_exp_f32_e32 v46, v46
	v_exp_f32_e32 v47, v47
	v_add_f32_e32 v45, 1.0, v45
	v_rcp_f32_e32 v48, v45
	v_add_f32_e32 v45, 1.0, v46
	v_add_f32_e32 v46, 1.0, v47
	v_mul_f32_e32 v47, 0xbfb8aa3b, v40
	v_mul_f32_e32 v49, 0xbfb8aa3b, v36
	v_exp_f32_e32 v47, v47
	v_exp_f32_e32 v50, v49
	v_rcp_f32_e32 v49, v46
	v_mul_f32_e32 v44, 0xbfb8aa3b, v38
	v_add_f32_e32 v46, 1.0, v47
	v_add_f32_e32 v47, 1.0, v50
	v_mul_f32_e32 v50, 0xbfb8aa3b, v41
	v_exp_f32_e32 v51, v50
	v_mul_f32_e32 v50, 0xbfb8aa3b, v37
	v_exp_f32_e32 v44, v44
	v_exp_f32_e32 v52, v50
	v_rcp_f32_e32 v50, v47
	v_add_f32_e32 v47, 1.0, v51
	v_add_f32_e32 v44, 1.0, v44
	v_add_f32_e32 v51, 1.0, v52
	v_rcp_f32_e32 v44, v44
	v_rcp_f32_e32 v45, v45
	v_rcp_f32_e32 v46, v46
	v_rcp_f32_e32 v47, v47
	v_rcp_f32_e32 v51, v51
	v_mov_b32_e32 v52, v58
	v_cvt_pk_bf16_f32 v34, v44, v45
	v_cvt_pk_bf16_f32 v35, v46, v47
	v_cvt_pk_bf16_f32 v36, v48, v49
	v_cvt_pk_bf16_f32 v37, v50, v51
	global_store_dwordx4 v[42:43], v[34:37], off offset:256
	s_nop 1
	v_mul_f32_e32 v35, 0xbfb8aa3b, v26
	v_exp_f32_e32 v35, v35
	v_mul_f32_e32 v36, 0xbfb8aa3b, v31
	v_mul_f32_e32 v37, 0xbfb8aa3b, v27
	v_exp_f32_e32 v36, v36
	v_exp_f32_e32 v37, v37
	v_add_f32_e32 v35, 1.0, v35
	v_rcp_f32_e32 v38, v35
	v_add_f32_e32 v35, 1.0, v36
	v_add_f32_e32 v36, 1.0, v37
	v_mul_f32_e32 v37, 0xbfb8aa3b, v32
	v_mul_f32_e32 v39, 0xbfb8aa3b, v28
	v_exp_f32_e32 v37, v37
	v_exp_f32_e32 v40, v39
	v_rcp_f32_e32 v39, v36
	v_mul_f32_e32 v34, 0xbfb8aa3b, v30
	v_add_f32_e32 v36, 1.0, v37
	v_add_f32_e32 v37, 1.0, v40
	v_mul_f32_e32 v40, 0xbfb8aa3b, v33
	v_exp_f32_e32 v41, v40
	v_mul_f32_e32 v40, 0xbfb8aa3b, v29
	v_exp_f32_e32 v34, v34
	v_exp_f32_e32 v42, v40
	v_rcp_f32_e32 v40, v37
	v_add_f32_e32 v37, 1.0, v41
	v_add_f32_e32 v34, 1.0, v34
	v_add_f32_e32 v41, 1.0, v42
	v_rcp_f32_e32 v34, v34
	v_rcp_f32_e32 v35, v35
	v_rcp_f32_e32 v36, v36
	v_rcp_f32_e32 v37, v37
	v_rcp_f32_e32 v41, v41
	v_mov_b32_e32 v42, v52
	v_add_u32_e32 v26, 0xa0, v161
	v_mad_i64_i32 v[26:27], s[72:73], s70, v26, 0
	v_lshl_add_u64 v[26:27], v[26:27], 1, v[122:123]
	v_cvt_pk_bf16_f32 v28, v34, v35
	v_cvt_pk_bf16_f32 v29, v36, v37
	v_cvt_pk_bf16_f32 v30, v38, v39
	v_cvt_pk_bf16_f32 v31, v40, v41
	global_store_dwordx4 v[26:27], v[28:31], off
	s_nop 1
	v_mul_f32_e32 v29, 0xbfb8aa3b, v18
	v_exp_f32_e32 v29, v29
	v_mul_f32_e32 v30, 0xbfb8aa3b, v23
	v_mul_f32_e32 v31, 0xbfb8aa3b, v19
	v_exp_f32_e32 v30, v30
	v_exp_f32_e32 v31, v31
	v_add_f32_e32 v29, 1.0, v29
	v_rcp_f32_e32 v32, v29
	v_add_f32_e32 v29, 1.0, v30
	v_add_f32_e32 v30, 1.0, v31
	v_mul_f32_e32 v31, 0xbfb8aa3b, v24
	v_mul_f32_e32 v33, 0xbfb8aa3b, v20
	v_exp_f32_e32 v31, v31
	v_exp_f32_e32 v34, v33
	v_rcp_f32_e32 v33, v30
	v_mul_f32_e32 v28, 0xbfb8aa3b, v22
	v_add_f32_e32 v30, 1.0, v31
	v_add_f32_e32 v31, 1.0, v34
	v_mul_f32_e32 v34, 0xbfb8aa3b, v25
	v_exp_f32_e32 v35, v34
	v_mul_f32_e32 v34, 0xbfb8aa3b, v21
	v_exp_f32_e32 v28, v28
	v_exp_f32_e32 v36, v34
	v_rcp_f32_e32 v34, v31
	v_add_f32_e32 v31, 1.0, v35
	v_add_f32_e32 v28, 1.0, v28
	v_add_f32_e32 v35, 1.0, v36
	v_rcp_f32_e32 v28, v28
	v_rcp_f32_e32 v29, v29
	v_rcp_f32_e32 v30, v30
	v_rcp_f32_e32 v31, v31
	v_rcp_f32_e32 v35, v35
	v_mov_b32_e32 v36, v42
	v_cvt_pk_bf16_f32 v18, v28, v29
	v_cvt_pk_bf16_f32 v19, v30, v31
	v_cvt_pk_bf16_f32 v20, v32, v33
	v_cvt_pk_bf16_f32 v21, v34, v35
	global_store_dwordx4 v[26:27], v[18:21], off offset:256
	s_nop 1
	v_mul_f32_e32 v19, 0xbfb8aa3b, v10
	v_exp_f32_e32 v19, v19
	v_mul_f32_e32 v20, 0xbfb8aa3b, v15
	v_mul_f32_e32 v21, 0xbfb8aa3b, v11
	v_exp_f32_e32 v20, v20
	v_exp_f32_e32 v21, v21
	v_add_f32_e32 v19, 1.0, v19
	v_rcp_f32_e32 v22, v19
	v_add_f32_e32 v19, 1.0, v20
	v_add_f32_e32 v20, 1.0, v21
	v_mul_f32_e32 v21, 0xbfb8aa3b, v16
	v_mul_f32_e32 v23, 0xbfb8aa3b, v12
	v_exp_f32_e32 v21, v21
	v_exp_f32_e32 v24, v23
	v_rcp_f32_e32 v23, v20
	v_mul_f32_e32 v18, 0xbfb8aa3b, v14
	v_add_f32_e32 v20, 1.0, v21
	v_add_f32_e32 v21, 1.0, v24
	v_mul_f32_e32 v24, 0xbfb8aa3b, v17
	v_exp_f32_e32 v25, v24
	v_mul_f32_e32 v24, 0xbfb8aa3b, v13
	v_exp_f32_e32 v18, v18
	v_exp_f32_e32 v26, v24
	v_rcp_f32_e32 v24, v21
	v_add_f32_e32 v21, 1.0, v25
	v_add_f32_e32 v18, 1.0, v18
	v_add_f32_e32 v25, 1.0, v26
	v_rcp_f32_e32 v18, v18
	v_rcp_f32_e32 v19, v19
	v_rcp_f32_e32 v20, v20
	v_rcp_f32_e32 v21, v21
	v_rcp_f32_e32 v25, v25
	v_mov_b32_e32 v26, v36
	s_mov_b64 s[72:73], 0
	v_add_u32_e32 v10, 0xb0, v161
	v_mad_i64_i32 v[10:11], s[70:71], s70, v10, 0
	v_lshl_add_u64 v[10:11], v[10:11], 1, v[122:123]
	v_cvt_pk_bf16_f32 v12, v18, v19
	v_cvt_pk_bf16_f32 v13, v20, v21
	v_cvt_pk_bf16_f32 v14, v22, v23
	v_cvt_pk_bf16_f32 v15, v24, v25
	global_store_dwordx4 v[10:11], v[12:15], off
	s_mov_b64 s[6:7], -1
	s_nop 0
	v_mul_f32_e32 v13, 0xbfb8aa3b, v2
	v_exp_f32_e32 v13, v13
	v_mul_f32_e32 v14, 0xbfb8aa3b, v7
	v_mul_f32_e32 v15, 0xbfb8aa3b, v3
	v_exp_f32_e32 v14, v14
	v_exp_f32_e32 v15, v15
	v_add_f32_e32 v13, 1.0, v13
	v_rcp_f32_e32 v16, v13
	v_add_f32_e32 v13, 1.0, v14
	v_add_f32_e32 v14, 1.0, v15
	v_mul_f32_e32 v15, 0xbfb8aa3b, v8
	v_mul_f32_e32 v17, 0xbfb8aa3b, v4
	v_exp_f32_e32 v15, v15
	v_exp_f32_e32 v18, v17
	v_rcp_f32_e32 v17, v14
	v_mul_f32_e32 v12, 0xbfb8aa3b, v6
	v_add_f32_e32 v14, 1.0, v15
	v_add_f32_e32 v15, 1.0, v18
	v_mul_f32_e32 v18, 0xbfb8aa3b, v9
	v_exp_f32_e32 v19, v18
	v_mul_f32_e32 v18, 0xbfb8aa3b, v5
	v_exp_f32_e32 v12, v12
	v_exp_f32_e32 v20, v18
	v_rcp_f32_e32 v18, v15
	v_add_f32_e32 v15, 1.0, v19
	v_add_f32_e32 v12, 1.0, v12
	v_add_f32_e32 v19, 1.0, v20
	v_rcp_f32_e32 v12, v12
	v_rcp_f32_e32 v13, v13
	v_rcp_f32_e32 v14, v14
	v_rcp_f32_e32 v15, v15
	v_rcp_f32_e32 v19, v19
	v_mov_b32_e32 v20, v26
	s_mov_b64 s[8:9], 0
	s_and_b64 vcc, exec, s[54:55]
	v_cvt_pk_bf16_f32 v2, v12, v13
	v_cvt_pk_bf16_f32 v3, v14, v15
	v_cvt_pk_bf16_f32 v4, v16, v17
	v_cvt_pk_bf16_f32 v5, v18, v19
	global_store_dwordx4 v[10:11], v[2:5], off offset:256
	s_branch .LBB0_416
.Lmy_e1_act3:
	s_xor_b64 s[74:75], s[74:75], -1
	s_xor_b64 s[76:77], s[76:77], -1
	v_pk_mul_f32 v[148:149], v[128:129], s[20:21] op_sel_hi:[1,0]
	v_pk_mul_f32 v[146:147], v[126:127], s[20:21] op_sel_hi:[1,0]
	v_pk_mul_f32 v[152:153], v[124:125], s[20:21] op_sel_hi:[1,0]
	v_pk_mul_f32 v[150:151], v[122:123], s[20:21] op_sel_hi:[1,0]
	v_mov_b32_e32 v162, 0
	s_mov_b64 s[78:79], 0
	s_lshl_b32 s6, s6, 8
	s_add_i32 s6, s7, s6
	v_or_b32_e32 v122, s6, v156
	s_lshl_b32 s6, s72, 1
	s_add_u32 s6, s38, s6
	v_lshl_add_u32 v161, s8, 8, v154
	s_addc_u32 s7, s39, 0
	v_ashrrev_i32_e32 v123, 31, v122
	v_lshl_add_u64 v[122:123], v[122:123], 1, s[6:7]
	v_mad_i64_i32 v[124:125], s[6:7], s70, v161, 0
	v_lshl_add_u64 v[124:125], v[124:125], 1, v[122:123]
	v_cvt_pk_bf16_f32 v126, v146, v147
	v_cvt_pk_bf16_f32 v127, v148, v149
	v_cvt_pk_bf16_f32 v128, v150, v151
	v_cvt_pk_bf16_f32 v129, v152, v153
	global_store_dwordx4 v[124:125], v[126:129], off
	s_nop 1
	v_pk_mul_f32 v[128:129], v[120:121], s[20:21] op_sel_hi:[1,0]
	v_pk_mul_f32 v[126:127], v[118:119], s[20:21] op_sel_hi:[1,0]
	v_pk_mul_f32 v[148:149], v[116:117], s[20:21] op_sel_hi:[1,0]
	v_pk_mul_f32 v[146:147], v[114:115], s[20:21] op_sel_hi:[1,0]
	v_mov_b32_e32 v150, v162
	v_cvt_pk_bf16_f32 v114, v126, v127
	v_cvt_pk_bf16_f32 v115, v128, v129
	v_cvt_pk_bf16_f32 v116, v146, v147
	v_cvt_pk_bf16_f32 v117, v148, v149
	global_store_dwordx4 v[124:125], v[114:117], off offset:256
	s_nop 1
	v_pk_mul_f32 v[116:117], v[112:113], s[20:21] op_sel_hi:[1,0]
	v_pk_mul_f32 v[114:115], v[110:111], s[20:21] op_sel_hi:[1,0]
	v_pk_mul_f32 v[120:121], v[108:109], s[20:21] op_sel_hi:[1,0]
	v_pk_mul_f32 v[118:119], v[106:107], s[20:21] op_sel_hi:[1,0]
	v_mov_b32_e32 v124, v150
	v_or_b32_e32 v106, 16, v161
	v_mad_i64_i32 v[106:107], s[72:73], s70, v106, 0
	v_lshl_add_u64 v[106:107], v[106:107], 1, v[122:123]
	v_cvt_pk_bf16_f32 v108, v114, v115
	v_cvt_pk_bf16_f32 v109, v116, v117
	v_cvt_pk_bf16_f32 v110, v118, v119
	v_cvt_pk_bf16_f32 v111, v120, v121
	global_store_dwordx4 v[106:107], v[108:111], off
	s_nop 1
	v_pk_mul_f32 v[110:111], v[104:105], s[20:21] op_sel_hi:[1,0]
	v_pk_mul_f32 v[108:109], v[102:103], s[20:21] op_sel_hi:[1,0]
	v_pk_mul_f32 v[114:115], v[100:101], s[20:21] op_sel_hi:[1,0]
	v_pk_mul_f32 v[112:113], v[98:99], s[20:21] op_sel_hi:[1,0]
	v_mov_b32_e32 v116, v124
	v_cvt_pk_bf16_f32 v98, v108, v109
	v_cvt_pk_bf16_f32 v99, v110, v111
	v_cvt_pk_bf16_f32 v100, v112, v113
	v_cvt_pk_bf16_f32 v101, v114, v115
	global_store_dwordx4 v[106:107], v[98:101], off offset:256
	s_nop 1
	v_pk_mul_f32 v[100:101], v[96:97], s[20:21] op_sel_hi:[1,0]
	v_pk_mul_f32 v[98:99], v[94:95], s[20:21] op_sel_hi:[1,0]
	v_pk_mul_f32 v[104:105], v[92:93], s[20:21] op_sel_hi:[1,0]
	v_pk_mul_f32 v[102:103], v[90:91], s[20:21] op_sel_hi:[1,0]
	v_mov_b32_e32 v106, v116
	v_or_b32_e32 v90, 32, v161
	v_mad_i64_i32 v[90:91], s[72:73], s70, v90, 0
	v_lshl_add_u64 v[90:91], v[90:91], 1, v[122:123]
	v_cvt_pk_bf16_f32 v92, v98, v99
	v_cvt_pk_bf16_f32 v93, v100, v101
	v_cvt_pk_bf16_f32 v94, v102, v103
	v_cvt_pk_bf16_f32 v95, v104, v105
	global_store_dwordx4 v[90:91], v[92:95], off
	s_nop 1
	v_pk_mul_f32 v[94:95], v[88:89], s[20:21] op_sel_hi:[1,0]
	v_pk_mul_f32 v[92:93], v[86:87], s[20:21] op_sel_hi:[1,0]
	v_pk_mul_f32 v[98:99], v[84:85], s[20:21] op_sel_hi:[1,0]
	v_pk_mul_f32 v[96:97], v[82:83], s[20:21] op_sel_hi:[1,0]
	v_mov_b32_e32 v100, v106
	v_cvt_pk_bf16_f32 v82, v92, v93
	v_cvt_pk_bf16_f32 v83, v94, v95
	v_cvt_pk_bf16_f32 v84, v96, v97
	v_cvt_pk_bf16_f32 v85, v98, v99
	global_store_dwordx4 v[90:91], v[82:85], off offset:256
	s_nop 1
	v_pk_mul_f32 v[84:85], v[80:81], s[20:21] op_sel_hi:[1,0]
	v_pk_mul_f32 v[82:83], v[78:79], s[20:21] op_sel_hi:[1,0]
	v_pk_mul_f32 v[88:89], v[76:77], s[20:21] op_sel_hi:[1,0]
	v_pk_mul_f32 v[86:87], v[74:75], s[20:21] op_sel_hi:[1,0]
	v_mov_b32_e32 v90, v100
	v_or_b32_e32 v74, 48, v161
	v_mad_i64_i32 v[74:75], s[72:73], s70, v74, 0
	v_lshl_add_u64 v[74:75], v[74:75], 1, v[122:123]
	v_cvt_pk_bf16_f32 v76, v82, v83
	v_cvt_pk_bf16_f32 v77, v84, v85
	v_cvt_pk_bf16_f32 v78, v86, v87
	v_cvt_pk_bf16_f32 v79, v88, v89
	global_store_dwordx4 v[74:75], v[76:79], off
	s_nop 1
	v_pk_mul_f32 v[78:79], v[72:73], s[20:21] op_sel_hi:[1,0]
	v_pk_mul_f32 v[76:77], v[70:71], s[20:21] op_sel_hi:[1,0]
	v_pk_mul_f32 v[82:83], v[68:69], s[20:21] op_sel_hi:[1,0]
	v_pk_mul_f32 v[80:81], v[66:67], s[20:21] op_sel_hi:[1,0]
	v_mov_b32_e32 v84, v90
	v_cvt_pk_bf16_f32 v66, v76, v77
	v_cvt_pk_bf16_f32 v67, v78, v79
	v_cvt_pk_bf16_f32 v68, v80, v81
	v_cvt_pk_bf16_f32 v69, v82, v83
	global_store_dwordx4 v[74:75], v[66:69], off offset:256
	s_nop 1
	v_pk_mul_f32 v[68:69], v[64:65], s[20:21] op_sel_hi:[1,0]
	v_pk_mul_f32 v[66:67], v[62:63], s[20:21] op_sel_hi:[1,0]
	v_pk_mul_f32 v[72:73], v[60:61], s[20:21] op_sel_hi:[1,0]
	v_pk_mul_f32 v[70:71], v[58:59], s[20:21] op_sel_hi:[1,0]
	v_mov_b32_e32 v74, v84
	v_add_u32_e32 v58, 0x80, v161
	v_mad_i64_i32 v[58:59], s[72:73], s70, v58, 0
	v_lshl_add_u64 v[58:59], v[58:59], 1, v[122:123]
	v_cvt_pk_bf16_f32 v60, v66, v67
	v_cvt_pk_bf16_f32 v61, v68, v69
	v_cvt_pk_bf16_f32 v62, v70, v71
	v_cvt_pk_bf16_f32 v63, v72, v73
	global_store_dwordx4 v[58:59], v[60:63], off
	s_nop 1
	v_pk_mul_f32 v[62:63], v[56:57], s[20:21] op_sel_hi:[1,0]
	v_pk_mul_f32 v[60:61], v[54:55], s[20:21] op_sel_hi:[1,0]
	v_pk_mul_f32 v[66:67], v[52:53], s[20:21] op_sel_hi:[1,0]
	v_pk_mul_f32 v[64:65], v[50:51], s[20:21] op_sel_hi:[1,0]
	v_mov_b32_e32 v68, v74
	v_cvt_pk_bf16_f32 v50, v60, v61
	v_cvt_pk_bf16_f32 v51, v62, v63
	v_cvt_pk_bf16_f32 v52, v64, v65
	v_cvt_pk_bf16_f32 v53, v66, v67
	global_store_dwordx4 v[58:59], v[50:53], off offset:256
	s_nop 1
	v_pk_mul_f32 v[52:53], v[48:49], s[20:21] op_sel_hi:[1,0]
	v_pk_mul_f32 v[50:51], v[46:47], s[20:21] op_sel_hi:[1,0]
	v_pk_mul_f32 v[56:57], v[44:45], s[20:21] op_sel_hi:[1,0]
	v_pk_mul_f32 v[54:55], v[42:43], s[20:21] op_sel_hi:[1,0]
	v_mov_b32_e32 v58, v68
	v_add_u32_e32 v42, 0x90, v161
	v_mad_i64_i32 v[42:43], s[72:73], s70, v42, 0
	v_lshl_add_u64 v[42:43], v[42:43], 1, v[122:123]
	v_cvt_pk_bf16_f32 v44, v50, v51
	v_cvt_pk_bf16_f32 v45, v52, v53
	v_cvt_pk_bf16_f32 v46, v54, v55
	v_cvt_pk_bf16_f32 v47, v56, v57
	global_store_dwordx4 v[42:43], v[44:47], off
	s_nop 1
	v_pk_mul_f32 v[46:47], v[40:41], s[20:21] op_sel_hi:[1,0]
	v_pk_mul_f32 v[44:45], v[38:39], s[20:21] op_sel_hi:[1,0]
	v_pk_mul_f32 v[50:51], v[36:37], s[20:21] op_sel_hi:[1,0]
	v_pk_mul_f32 v[48:49], v[34:35], s[20:21] op_sel_hi:[1,0]
	v_mov_b32_e32 v52, v58
	v_cvt_pk_bf16_f32 v34, v44, v45
	v_cvt_pk_bf16_f32 v35, v46, v47
	v_cvt_pk_bf16_f32 v36, v48, v49
	v_cvt_pk_bf16_f32 v37, v50, v51
	global_store_dwordx4 v[42:43], v[34:37], off offset:256
	s_nop 1
	v_pk_mul_f32 v[36:37], v[32:33], s[20:21] op_sel_hi:[1,0]
	v_pk_mul_f32 v[34:35], v[30:31], s[20:21] op_sel_hi:[1,0]
	v_pk_mul_f32 v[40:41], v[28:29], s[20:21] op_sel_hi:[1,0]
	v_pk_mul_f32 v[38:39], v[26:27], s[20:21] op_sel_hi:[1,0]
	v_mov_b32_e32 v42, v52
	v_add_u32_e32 v26, 0xa0, v161
	v_mad_i64_i32 v[26:27], s[72:73], s70, v26, 0
	v_lshl_add_u64 v[26:27], v[26:27], 1, v[122:123]
	v_cvt_pk_bf16_f32 v28, v34, v35
	v_cvt_pk_bf16_f32 v29, v36, v37
	v_cvt_pk_bf16_f32 v30, v38, v39
	v_cvt_pk_bf16_f32 v31, v40, v41
	global_store_dwordx4 v[26:27], v[28:31], off
	s_nop 1
	v_pk_mul_f32 v[30:31], v[24:25], s[20:21] op_sel_hi:[1,0]
	v_pk_mul_f32 v[28:29], v[22:23], s[20:21] op_sel_hi:[1,0]
	v_pk_mul_f32 v[34:35], v[20:21], s[20:21] op_sel_hi:[1,0]
	v_pk_mul_f32 v[32:33], v[18:19], s[20:21] op_sel_hi:[1,0]
	v_mov_b32_e32 v36, v42
	v_cvt_pk_bf16_f32 v18, v28, v29
	v_cvt_pk_bf16_f32 v19, v30, v31
	v_cvt_pk_bf16_f32 v20, v32, v33
	v_cvt_pk_bf16_f32 v21, v34, v35
	global_store_dwordx4 v[26:27], v[18:21], off offset:256
	s_nop 1
	v_pk_mul_f32 v[20:21], v[16:17], s[20:21] op_sel_hi:[1,0]
	v_pk_mul_f32 v[18:19], v[14:15], s[20:21] op_sel_hi:[1,0]
	v_pk_mul_f32 v[24:25], v[12:13], s[20:21] op_sel_hi:[1,0]
	v_pk_mul_f32 v[22:23], v[10:11], s[20:21] op_sel_hi:[1,0]
	v_mov_b32_e32 v26, v36
	s_mov_b64 s[72:73], 0
	v_add_u32_e32 v10, 0xb0, v161
	v_mad_i64_i32 v[10:11], s[70:71], s70, v10, 0
	v_lshl_add_u64 v[10:11], v[10:11], 1, v[122:123]
	v_cvt_pk_bf16_f32 v12, v18, v19
	v_cvt_pk_bf16_f32 v13, v20, v21
	v_cvt_pk_bf16_f32 v14, v22, v23
	v_cvt_pk_bf16_f32 v15, v24, v25
	global_store_dwordx4 v[10:11], v[12:15], off
	s_nop 1
	v_pk_mul_f32 v[14:15], v[8:9], s[20:21] op_sel_hi:[1,0]
	v_pk_mul_f32 v[12:13], v[6:7], s[20:21] op_sel_hi:[1,0]
	v_pk_mul_f32 v[18:19], v[4:5], s[20:21] op_sel_hi:[1,0]
	v_pk_mul_f32 v[16:17], v[2:3], s[20:21] op_sel_hi:[1,0]
	v_mov_b32_e32 v20, v26
	s_mov_b64 s[6:7], 0
	s_mov_b64 s[8:9], 0
	s_and_b64 vcc, exec, s[54:55]
	v_cvt_pk_bf16_f32 v2, v12, v13
	v_cvt_pk_bf16_f32 v3, v14, v15
	v_cvt_pk_bf16_f32 v4, v16, v17
	v_cvt_pk_bf16_f32 v5, v18, v19
	global_store_dwordx4 v[10:11], v[2:5], off offset:256
	s_branch .LBB0_416
